# GEMM unit entry: first K-loop trip peeled with SrcC=0 for the first MFMA into each accumulator; the 128-instruction accumulator zeroing in front of every unit removed
# speedup vs baseline: 1.0043x; 1.0012x over previous
; #define PG8_STAGE(bufoff, gbase, voff) do { _Pragma("unroll") for (int _i = 0; _i < 2; ++_i) \
;         __builtin_amdgcn_global_load_lds((const unsigned*)((const char*)(gbase) + (voff)[_i]), (PG8_LAS unsigned*)(lds + (bufoff) + ldsw + _i * 8192), 16, 0, 0); } while (0)
; #define PG8_LDA(dst, b, h) do { _Pragma("unroll") for (int m = 0; m < 4; ++m) _Pragma("unroll") for (int k = 0; k < 2; ++k) dst[m][k] = *(const PG8_LAS bf16x8*)(lds + PG8_SA(b, h) + aoff + m * 2048 + k * 1024); } while (0)
; #define PG8_LDB(dst, b, h) do { _Pragma("unroll") for (int n = 0; n < 2; ++n) _Pragma("unroll") for (int k = 0; k < 2; ++k) dst[n][k] = *(const PG8_LAS bf16x8*)(lds + PG8_SB(b, h) + boff + n * 2048 + k * 1024); } while (0)
; template <class Epi, class Sched, bool ALIGN_EPI = false, bool SP2 = false>
; __device__ __forceinline__ void gemm_phase(PG8_LAS unsigned char* lds, const Gemm g, const Sched& S, const Epi& E) {
;     ...
;         const bool has_next = S.next(ui + 1, nxt);
;         const char* nA = has_next ? (const char*)g.A + (size_t)nxt.pm * tstep : cA; const char* nB = has_next ? (const char*)g.Bt + (size_t)nxt.pn * tstep : cB;
;         for (int t = 0; t < nt; t += 2) {
;             const bool last = (t == nt - 2);
;             const char* a1 = cA + (size_t)(t + 1) * kstep;
;             const char* a2 = last ? nA : cA + (size_t)(t + 2) * kstep; const char* b2 = last ? nB : cB + (size_t)(t + 2) * kstep;
;             const char* a3 = a2 + kstep; const char* b3 = b2 + kstep;
;             if (last && has_next) S.a_ready(nxt);
;             if constexpr (SP2) {
;             PG8_LDB(B0, 0, 0); PG8_LDB(B1, 0, 1); PG8_SCHED; PG8_LDA(At, 0, 0); PG8_STAGE(PG8_SA(1, 1), a1 + hstep, voffA);
;             PG8_WAIT_V(8); PG8_WAIT_L(0); PG8_BAR; PG8_MMA(0, 0, At, B0); PG8_MMA(0, 1, At, B1); PG8_BAR; PG8_SCHED;
;             PG8_LDA(At, 0, 1); PG8_STAGE(PG8_SB(0, 0), b2, voffB); PG8_STAGE(PG8_SB(0, 1), b2 + hstep, voffB); PG8_STAGE(PG8_SA(0, 0), a2, voffA);
;             PG8_WAIT_V(8); PG8_WAIT_L(0); PG8_BAR; PG8_MMA(1, 0, At, B0); PG8_MMA(1, 1, At, B1); PG8_BAR; PG8_SCHED;
;     ...
; #pragma unroll
;         for (int a = 0; a < 2; ++a)
; #pragma unroll
;             for (int b = 0; b < 2; ++b)
; #pragma unroll
;                 for (int m = 0; m < 4; ++m)
; #pragma unroll
;                     for (int n = 0; n < 2; ++n) acc[a][b][m][n] = (f32x4){0.f, 0.f, 0.f, 0.f};
.LBB0_131:
	s_ashr_i32 s35, s34, 31
	s_lshl_b64 s[38:39], s[34:35], 21
	s_add_u32 s38, s51, s38
	s_addc_u32 s39, s52, s39
	s_and_b64 s[40:41], s[36:37], exec
	s_cselect_b32 s35, s39, s3
	s_cselect_b32 s43, s38, s2
	s_ashr_i32 s17, s16, 31
	s_lshl_b64 s[40:41], s[16:17], 21
	s_add_u32 s40, s53, s40
	s_addc_u32 s41, s54, s41
	s_and_b64 s[48:49], s[36:37], exec
	s_cselect_b32 s17, s41, s47
	s_cselect_b32 s79, s40, s46
	s_add_u32 s2, s2, 0x100080
	s_addc_u32 s3, s3, 0
	s_add_u32 s80, s46, 0x100
	s_addc_u32 s81, s47, 0
	s_mov_b32 s82, -2
	ds_read_b128 v[152:155], v171
	ds_read_b128 v[176:179], v171 offset:1024
	ds_read_b128 v[180:183], v171 offset:2048
	ds_read_b128 v[184:187], v171 offset:3072
	ds_read_b128 v[188:191], v172
	ds_read_b128 v[192:195], v172 offset:1024
	ds_read_b128 v[198:201], v172 offset:2048
	ds_read_b128 v[202:205], v172 offset:3072
	s_add_u32 s46, s2, 0xfff00080
	s_addc_u32 s47, s3, -1
	s_cmp_eq_u32 s82, 60
	s_cselect_b32 s49, s35, s47
	s_cselect_b32 s48, s43, s46
	s_cselect_b32 s47, s17, s81
	s_cselect_b32 s46, s79, s80
	v_lshl_add_u64 v[156:157], s[2:3], 0, v[144:145]
	s_add_i32 m0, s45, 0xc000
	ds_read_b128 v[206:209], v173
	ds_read_b128 v[210:213], v173 offset:1024
	ds_read_b128 v[214:217], v173 offset:2048
	ds_read_b128 v[218:221], v173 offset:3072
	ds_read_b128 v[222:225], v173 offset:4096
	ds_read_b128 v[226:229], v173 offset:5120
	ds_read_b128 v[230:233], v173 offset:6144
	ds_read_b128 v[234:237], v173 offset:7168
	global_load_lds_dwordx4 v[156:157], off
	v_lshl_add_u64 v[156:157], s[2:3], 0, v[146:147]
	s_add_i32 m0, s45, 0xe000
	s_nop 0
	global_load_lds_dwordx4 v[156:157], off
	s_waitcnt vmcnt(8)
	s_waitcnt lgkmcnt(0)
	s_setprio 1
	s_barrier
	v_mfma_f32_16x16x32_bf16 v[126:129], v[152:155], v[206:209], 0
	v_mfma_f32_16x16x32_bf16 v[122:125], v[180:183], v[206:209], 0
	v_mfma_f32_16x16x32_bf16 v[110:113], v[152:155], v[214:217], 0
	v_mfma_f32_16x16x32_bf16 v[106:109], v[180:183], v[214:217], 0
	v_mfma_f32_16x16x32_bf16 v[94:97], v[152:155], v[222:225], 0
	v_mfma_f32_16x16x32_bf16 v[90:93], v[180:183], v[222:225], 0
	v_mfma_f32_16x16x32_bf16 v[78:81], v[152:155], v[230:233], 0
	v_mfma_f32_16x16x32_bf16 v[74:77], v[180:183], v[230:233], 0
	v_mfma_f32_16x16x32_bf16 v[126:129], v[176:179], v[210:213], v[126:129]
	v_mfma_f32_16x16x32_bf16 v[122:125], v[184:187], v[210:213], v[122:125]
	v_mfma_f32_16x16x32_bf16 v[110:113], v[176:179], v[218:221], v[110:113]
	v_mfma_f32_16x16x32_bf16 v[106:109], v[184:187], v[218:221], v[106:109]
	v_mfma_f32_16x16x32_bf16 v[94:97], v[176:179], v[226:229], v[94:97]
	v_mfma_f32_16x16x32_bf16 v[90:93], v[184:187], v[226:229], v[90:93]
	v_mfma_f32_16x16x32_bf16 v[78:81], v[176:179], v[234:237], v[78:81]
	v_mfma_f32_16x16x32_bf16 v[74:77], v[184:187], v[234:237], v[74:77]
	s_setprio 0
	s_setprio 1
	v_mfma_f32_16x16x32_bf16 v[118:121], v[188:191], v[206:209], 0
	v_mfma_f32_16x16x32_bf16 v[114:117], v[198:201], v[206:209], 0
	v_mfma_f32_16x16x32_bf16 v[102:105], v[188:191], v[214:217], 0
	v_mfma_f32_16x16x32_bf16 v[98:101], v[198:201], v[214:217], 0
	v_mfma_f32_16x16x32_bf16 v[86:89], v[188:191], v[222:225], 0
	v_mfma_f32_16x16x32_bf16 v[82:85], v[198:201], v[222:225], 0
	v_mfma_f32_16x16x32_bf16 v[70:73], v[188:191], v[230:233], 0
	v_mfma_f32_16x16x32_bf16 v[66:69], v[198:201], v[230:233], 0
	v_mfma_f32_16x16x32_bf16 v[118:121], v[192:195], v[210:213], v[118:121]
	v_mfma_f32_16x16x32_bf16 v[114:117], v[202:205], v[210:213], v[114:117]
	v_mfma_f32_16x16x32_bf16 v[102:105], v[192:195], v[218:221], v[102:105]
	v_mfma_f32_16x16x32_bf16 v[98:101], v[202:205], v[218:221], v[98:101]
	v_mfma_f32_16x16x32_bf16 v[86:89], v[192:195], v[226:229], v[86:89]
	v_mfma_f32_16x16x32_bf16 v[82:85], v[202:205], v[226:229], v[82:85]
	v_mfma_f32_16x16x32_bf16 v[70:73], v[192:195], v[234:237], v[70:73]
	v_mfma_f32_16x16x32_bf16 v[66:69], v[202:205], v[234:237], v[66:69]
	s_setprio 0
	s_barrier
	s_add_i32 s83, s74, s55
	v_lshl_add_u64 v[156:157], s[46:47], 0, v[132:133]
	s_mov_b32 m0, s83
	ds_read_b128 v[206:209], v173 offset:16384
	ds_read_b128 v[210:213], v173 offset:17408
	ds_read_b128 v[214:217], v173 offset:18432
	ds_read_b128 v[218:221], v173 offset:19456
	ds_read_b128 v[222:225], v173 offset:20480
	ds_read_b128 v[226:229], v173 offset:21504
	ds_read_b128 v[230:233], v173 offset:22528
	ds_read_b128 v[234:237], v173 offset:23552
	global_load_lds_dwordx4 v[156:157], off
	s_add_i32 m0, s83, 0x2000
	s_add_u32 s84, s46, 0x100000
	v_lshl_add_u64 v[238:239], s[46:47], 0, v[136:137]
	s_addc_u32 s85, s47, 0
	s_add_i32 s83, s75, s55
	global_load_lds_dwordx4 v[238:239], off
	v_lshl_add_u64 v[240:241], s[84:85], 0, v[132:133]
	s_mov_b32 m0, s83
	v_lshl_add_u64 v[242:243], s[48:49], 0, v[134:135]
	global_load_lds_dwordx4 v[240:241], off
	v_lshl_add_u64 v[240:241], s[84:85], 0, v[136:137]
	s_add_i32 m0, s83, 0x2000
	s_nop 0
	global_load_lds_dwordx4 v[240:241], off
	v_lshl_add_u64 v[240:241], s[48:49], 0, v[130:131]
	s_mov_b32 m0, s45
	s_nop 0
	global_load_lds_dwordx4 v[240:241], off
	s_mov_b32 m0, s56
	s_nop 0
	global_load_lds_dwordx4 v[242:243], off
	s_waitcnt vmcnt(8)
	s_waitcnt lgkmcnt(0)
	s_setprio 1
	s_barrier
; #define PG8_STAGE(bufoff, gbase, voff) do { _Pragma("unroll") for (int _i = 0; _i < 2; ++_i) \
;         __builtin_amdgcn_global_load_lds((const unsigned*)((const char*)(gbase) + (voff)[_i]), (PG8_LAS unsigned*)(lds + (bufoff) + ldsw + _i * 8192), 16, 0, 0); } while (0)
; #define PG8_LDA(dst, b, h) do { _Pragma("unroll") for (int m = 0; m < 4; ++m) _Pragma("unroll") for (int k = 0; k < 2; ++k) dst[m][k] = *(const PG8_LAS bf16x8*)(lds + PG8_SA(b, h) + aoff + m * 2048 + k * 1024); } while (0)
; #define PG8_LDB(dst, b, h) do { _Pragma("unroll") for (int n = 0; n < 2; ++n) _Pragma("unroll") for (int k = 0; k < 2; ++k) dst[n][k] = *(const PG8_LAS bf16x8*)(lds + PG8_SB(b, h) + boff + n * 2048 + k * 1024); } while (0)
; #define PG8_MMA(ai, bj, At, Bt) do { __builtin_amdgcn_s_setprio(1); _Pragma("unroll") for (int m = 0; m < 4; ++m) _Pragma("unroll") for (int n = 0; n < 2; ++n) _Pragma("unroll") for (int k = 0; k < 2; ++k) \
;         acc[ai][bj][m][n] = __builtin_amdgcn_mfma_f32_16x16x32_bf16(Bt[n][k], At[m][k], acc[ai][bj][m][n], 0, 0, 0); __builtin_amdgcn_s_setprio(0); } while (0)
; #define PG8_WAIT_V(n) asm volatile("s_waitcnt vmcnt(" #n ")" ::: "memory")
; #define PG8_WAIT_L(n) asm volatile("s_waitcnt lgkmcnt(" #n ")" ::: "memory")
; #define PG8_BAR __builtin_amdgcn_s_barrier()
; #define PG8_SCHED __builtin_amdgcn_sched_barrier(0)
; template <class Epi, class Sched, bool ALIGN_EPI = false, bool SP2 = false>
; __device__ __forceinline__ void gemm_phase(PG8_LAS unsigned char* lds, const Gemm g, const Sched& S, const Epi& E) {
;     ...
;             PG8_WAIT_V(8); PG8_WAIT_L(0); PG8_BAR; PG8_MMA(1, 0, At, B0); PG8_MMA(1, 1, At, B1); PG8_BAR; PG8_SCHED;
;             PG8_LDB(B0, 1, 0); PG8_LDB(B1, 1, 1); PG8_SCHED; PG8_LDA(At, 1, 0); PG8_STAGE(PG8_SA(0, 1), a2 + hstep, voffA);
;             PG8_WAIT_V(8); PG8_WAIT_L(0); PG8_BAR; PG8_MMA(0, 0, At, B0); PG8_MMA(0, 1, At, B1); PG8_BAR; PG8_SCHED;
	v_mfma_f32_16x16x32_bf16 v[62:65], v[152:155], v[206:209], 0
	v_mfma_f32_16x16x32_bf16 v[58:61], v[180:183], v[206:209], 0
	v_mfma_f32_16x16x32_bf16 v[46:49], v[152:155], v[214:217], 0
	v_mfma_f32_16x16x32_bf16 v[42:45], v[180:183], v[214:217], 0
	v_mfma_f32_16x16x32_bf16 v[30:33], v[152:155], v[222:225], 0
	v_mfma_f32_16x16x32_bf16 v[26:29], v[180:183], v[222:225], 0
	v_mfma_f32_16x16x32_bf16 v[14:17], v[152:155], v[230:233], 0
	v_mfma_f32_16x16x32_bf16 v[10:13], v[180:183], v[230:233], 0
	v_mfma_f32_16x16x32_bf16 v[62:65], v[176:179], v[210:213], v[62:65]
	v_mfma_f32_16x16x32_bf16 v[58:61], v[184:187], v[210:213], v[58:61]
	v_mfma_f32_16x16x32_bf16 v[46:49], v[176:179], v[218:221], v[46:49]
	v_mfma_f32_16x16x32_bf16 v[42:45], v[184:187], v[218:221], v[42:45]
	v_mfma_f32_16x16x32_bf16 v[30:33], v[176:179], v[226:229], v[30:33]
	v_mfma_f32_16x16x32_bf16 v[26:29], v[184:187], v[226:229], v[26:29]
	v_mfma_f32_16x16x32_bf16 v[14:17], v[176:179], v[234:237], v[14:17]
	v_mfma_f32_16x16x32_bf16 v[10:13], v[184:187], v[234:237], v[10:13]
	s_setprio 0
	s_setprio 1
	v_mfma_f32_16x16x32_bf16 v[54:57], v[188:191], v[206:209], 0
	v_mfma_f32_16x16x32_bf16 v[50:53], v[198:201], v[206:209], 0
	v_mfma_f32_16x16x32_bf16 v[38:41], v[188:191], v[214:217], 0
	v_mfma_f32_16x16x32_bf16 v[34:37], v[198:201], v[214:217], 0
	v_mfma_f32_16x16x32_bf16 v[22:25], v[188:191], v[222:225], 0
	v_mfma_f32_16x16x32_bf16 v[18:21], v[198:201], v[222:225], 0
	v_mfma_f32_16x16x32_bf16 v[6:9], v[188:191], v[230:233], 0
	v_mfma_f32_16x16x32_bf16 v[2:5], v[198:201], v[230:233], 0
	v_mfma_f32_16x16x32_bf16 v[54:57], v[192:195], v[210:213], v[54:57]
	v_mfma_f32_16x16x32_bf16 v[50:53], v[202:205], v[210:213], v[50:53]
	v_mfma_f32_16x16x32_bf16 v[38:41], v[192:195], v[218:221], v[38:41]
	v_mfma_f32_16x16x32_bf16 v[34:37], v[202:205], v[218:221], v[34:37]
	v_mfma_f32_16x16x32_bf16 v[22:25], v[192:195], v[226:229], v[22:25]
	v_mfma_f32_16x16x32_bf16 v[18:21], v[202:205], v[226:229], v[18:21]
	v_mfma_f32_16x16x32_bf16 v[6:9], v[192:195], v[234:237], v[6:9]
	v_mfma_f32_16x16x32_bf16 v[2:5], v[202:205], v[234:237], v[2:5]
	s_setprio 0
	s_barrier
	s_add_i32 s83, 0, 0x18000
	v_add_u32_e32 v149, s83, v167
	s_add_i32 s84, 0, 0x1c000
	ds_read_b128 v[152:155], v149
	ds_read_b128 v[176:179], v149 offset:1024
	ds_read_b128 v[180:183], v149 offset:2048
	ds_read_b128 v[184:187], v149 offset:3072
	v_add_u32_e32 v149, s84, v167
	ds_read_b128 v[188:191], v149
	ds_read_b128 v[192:195], v149 offset:1024
	ds_read_b128 v[198:201], v149 offset:2048
	ds_read_b128 v[202:205], v149 offset:3072
	s_add_u32 s48, s48, 0x100000
	s_addc_u32 s49, s49, 0
	s_mov_b32 m0, s57
	v_lshl_add_u64 v[244:245], s[48:49], 0, v[130:131]
	ds_read_b128 v[206:209], v173 offset:32768
	ds_read_b128 v[210:213], v173 offset:33792
	ds_read_b128 v[214:217], v173 offset:34816
	ds_read_b128 v[218:221], v173 offset:35840
	ds_read_b128 v[222:225], v173 offset:36864
	ds_read_b128 v[226:229], v173 offset:37888
	ds_read_b128 v[230:233], v173 offset:38912
	ds_read_b128 v[234:237], v173 offset:39936
	global_load_lds_dwordx4 v[244:245], off
	v_lshl_add_u64 v[244:245], s[48:49], 0, v[134:135]
	s_mov_b32 m0, s58
	s_nop 0
	global_load_lds_dwordx4 v[244:245], off
	s_waitcnt vmcnt(8)
	s_waitcnt lgkmcnt(0)
	s_setprio 1
	s_barrier
	v_mfma_f32_16x16x32_bf16 v[126:129], v[152:155], v[206:209], v[126:129]
	v_mfma_f32_16x16x32_bf16 v[122:125], v[180:183], v[206:209], v[122:125]
	v_mfma_f32_16x16x32_bf16 v[110:113], v[152:155], v[214:217], v[110:113]
	v_mfma_f32_16x16x32_bf16 v[106:109], v[180:183], v[214:217], v[106:109]
	v_mfma_f32_16x16x32_bf16 v[94:97], v[152:155], v[222:225], v[94:97]
	v_mfma_f32_16x16x32_bf16 v[90:93], v[180:183], v[222:225], v[90:93]
	v_mfma_f32_16x16x32_bf16 v[78:81], v[152:155], v[230:233], v[78:81]
	v_mfma_f32_16x16x32_bf16 v[74:77], v[180:183], v[230:233], v[74:77]
	v_mfma_f32_16x16x32_bf16 v[126:129], v[176:179], v[210:213], v[126:129]
	v_mfma_f32_16x16x32_bf16 v[122:125], v[184:187], v[210:213], v[122:125]
	v_mfma_f32_16x16x32_bf16 v[110:113], v[176:179], v[218:221], v[110:113]
	v_mfma_f32_16x16x32_bf16 v[106:109], v[184:187], v[218:221], v[106:109]
	v_mfma_f32_16x16x32_bf16 v[94:97], v[176:179], v[226:229], v[94:97]
	v_mfma_f32_16x16x32_bf16 v[90:93], v[184:187], v[226:229], v[90:93]
	v_mfma_f32_16x16x32_bf16 v[78:81], v[176:179], v[234:237], v[78:81]
	v_mfma_f32_16x16x32_bf16 v[74:77], v[184:187], v[234:237], v[74:77]
	s_setprio 0
	s_setprio 1
	v_mfma_f32_16x16x32_bf16 v[118:121], v[188:191], v[206:209], v[118:121]
	v_mfma_f32_16x16x32_bf16 v[114:117], v[198:201], v[206:209], v[114:117]
	v_mfma_f32_16x16x32_bf16 v[102:105], v[188:191], v[214:217], v[102:105]
	v_mfma_f32_16x16x32_bf16 v[98:101], v[198:201], v[214:217], v[98:101]
	v_mfma_f32_16x16x32_bf16 v[86:89], v[188:191], v[222:225], v[86:89]
	v_mfma_f32_16x16x32_bf16 v[82:85], v[198:201], v[222:225], v[82:85]
	v_mfma_f32_16x16x32_bf16 v[70:73], v[188:191], v[230:233], v[70:73]
	v_mfma_f32_16x16x32_bf16 v[66:69], v[198:201], v[230:233], v[66:69]
	v_mfma_f32_16x16x32_bf16 v[118:121], v[192:195], v[210:213], v[118:121]
	v_mfma_f32_16x16x32_bf16 v[114:117], v[202:205], v[210:213], v[114:117]
	v_mfma_f32_16x16x32_bf16 v[102:105], v[192:195], v[218:221], v[102:105]
	v_mfma_f32_16x16x32_bf16 v[98:101], v[202:205], v[218:221], v[98:101]
	v_mfma_f32_16x16x32_bf16 v[86:89], v[192:195], v[226:229], v[86:89]
	v_mfma_f32_16x16x32_bf16 v[82:85], v[202:205], v[226:229], v[82:85]
	v_mfma_f32_16x16x32_bf16 v[70:73], v[192:195], v[234:237], v[70:73]
	v_mfma_f32_16x16x32_bf16 v[66:69], v[202:205], v[234:237], v[66:69]
	s_setprio 0
	s_barrier
; #define PG8_STAGE(bufoff, gbase, voff) do { _Pragma("unroll") for (int _i = 0; _i < 2; ++_i) \
;         __builtin_amdgcn_global_load_lds((const unsigned*)((const char*)(gbase) + (voff)[_i]), (PG8_LAS unsigned*)(lds + (bufoff) + ldsw + _i * 8192), 16, 0, 0); } while (0)
; #define PG8_LDA(dst, b, h) do { _Pragma("unroll") for (int m = 0; m < 4; ++m) _Pragma("unroll") for (int k = 0; k < 2; ++k) dst[m][k] = *(const PG8_LAS bf16x8*)(lds + PG8_SA(b, h) + aoff + m * 2048 + k * 1024); } while (0)
; #define PG8_MMA(ai, bj, At, Bt) do { __builtin_amdgcn_s_setprio(1); _Pragma("unroll") for (int m = 0; m < 4; ++m) _Pragma("unroll") for (int n = 0; n < 2; ++n) _Pragma("unroll") for (int k = 0; k < 2; ++k) \
;         acc[ai][bj][m][n] = __builtin_amdgcn_mfma_f32_16x16x32_bf16(Bt[n][k], At[m][k], acc[ai][bj][m][n], 0, 0, 0); __builtin_amdgcn_s_setprio(0); } while (0)
; #define PG8_WAIT_V(n) asm volatile("s_waitcnt vmcnt(" #n ")" ::: "memory")
; #define PG8_WAIT_L(n) asm volatile("s_waitcnt lgkmcnt(" #n ")" ::: "memory")
; #define PG8_BAR __builtin_amdgcn_s_barrier()
; #define PG8_SCHED __builtin_amdgcn_sched_barrier(0)
; template <class Epi, class Sched, bool ALIGN_EPI = false, bool SP2 = false>
; __device__ __forceinline__ void gemm_phase(PG8_LAS unsigned char* lds, const Gemm g, const Sched& S, const Epi& E) {
;     ...
;             PG8_LDA(At, 1, 1); PG8_STAGE(PG8_SB(1, 0), b3, voffB); PG8_STAGE(PG8_SB(1, 1), b3 + hstep, voffB); PG8_STAGE(PG8_SA(1, 0), a3, voffA);
;             PG8_WAIT_V(8); PG8_WAIT_L(0); PG8_BAR; PG8_MMA(1, 0, At, B0); PG8_MMA(1, 1, At, B1); PG8_BAR; PG8_SCHED;
	s_add_i32 s48, s83, s55
	v_lshl_add_u64 v[156:157], v[156:157], 0, s[10:11]
	s_mov_b32 m0, s48
	ds_read_b128 v[206:209], v173 offset:49152
	ds_read_b128 v[210:213], v173 offset:50176
	ds_read_b128 v[214:217], v173 offset:51200
	ds_read_b128 v[218:221], v173 offset:52224
	ds_read_b128 v[222:225], v173 offset:53248
	ds_read_b128 v[226:229], v173 offset:54272
	ds_read_b128 v[230:233], v173 offset:55296
	ds_read_b128 v[234:237], v173 offset:56320
	global_load_lds_dwordx4 v[156:157], off
	s_add_i32 m0, s48, 0x2000
	s_add_u32 s46, s46, 0x100080
	v_lshl_add_u64 v[156:157], v[238:239], 0, s[10:11]
	s_addc_u32 s47, s47, 0
	s_add_i32 s48, s84, s55
	global_load_lds_dwordx4 v[156:157], off
	v_lshl_add_u64 v[156:157], s[46:47], 0, v[132:133]
	s_mov_b32 m0, s48
	s_nop 0
	global_load_lds_dwordx4 v[156:157], off
	v_lshl_add_u64 v[156:157], s[46:47], 0, v[136:137]
	s_add_i32 m0, s48, 0x2000
	s_nop 0
	global_load_lds_dwordx4 v[156:157], off
	v_lshl_add_u64 v[156:157], v[240:241], 0, s[10:11]
	s_mov_b32 m0, s63
	s_nop 0
	global_load_lds_dwordx4 v[156:157], off
	v_lshl_add_u64 v[156:157], v[242:243], 0, s[10:11]
	s_mov_b32 m0, s70
	s_nop 0
	global_load_lds_dwordx4 v[156:157], off
	s_waitcnt vmcnt(8)
	s_waitcnt lgkmcnt(0)
	s_setprio 1
	s_barrier
	v_mfma_f32_16x16x32_bf16 v[62:65], v[152:155], v[206:209], v[62:65]
	v_mfma_f32_16x16x32_bf16 v[58:61], v[180:183], v[206:209], v[58:61]
	v_mfma_f32_16x16x32_bf16 v[46:49], v[152:155], v[214:217], v[46:49]
	v_mfma_f32_16x16x32_bf16 v[42:45], v[180:183], v[214:217], v[42:45]
	v_mfma_f32_16x16x32_bf16 v[30:33], v[152:155], v[222:225], v[30:33]
	v_mfma_f32_16x16x32_bf16 v[26:29], v[180:183], v[222:225], v[26:29]
	v_mfma_f32_16x16x32_bf16 v[14:17], v[152:155], v[230:233], v[14:17]
	v_mfma_f32_16x16x32_bf16 v[10:13], v[180:183], v[230:233], v[10:13]
	v_mfma_f32_16x16x32_bf16 v[62:65], v[176:179], v[210:213], v[62:65]
	v_mfma_f32_16x16x32_bf16 v[58:61], v[184:187], v[210:213], v[58:61]
	v_mfma_f32_16x16x32_bf16 v[46:49], v[176:179], v[218:221], v[46:49]
	v_mfma_f32_16x16x32_bf16 v[42:45], v[184:187], v[218:221], v[42:45]
	v_mfma_f32_16x16x32_bf16 v[30:33], v[176:179], v[226:229], v[30:33]
	v_mfma_f32_16x16x32_bf16 v[26:29], v[184:187], v[226:229], v[26:29]
	v_mfma_f32_16x16x32_bf16 v[14:17], v[176:179], v[234:237], v[14:17]
	v_mfma_f32_16x16x32_bf16 v[10:13], v[184:187], v[234:237], v[10:13]
	s_setprio 0
	s_setprio 1
	v_mfma_f32_16x16x32_bf16 v[54:57], v[188:191], v[206:209], v[54:57]
	v_mfma_f32_16x16x32_bf16 v[50:53], v[198:201], v[206:209], v[50:53]
	v_mfma_f32_16x16x32_bf16 v[38:41], v[188:191], v[214:217], v[38:41]
	v_mfma_f32_16x16x32_bf16 v[34:37], v[198:201], v[214:217], v[34:37]
	v_mfma_f32_16x16x32_bf16 v[22:25], v[188:191], v[222:225], v[22:25]
	v_mfma_f32_16x16x32_bf16 v[18:21], v[198:201], v[222:225], v[18:21]
	v_mfma_f32_16x16x32_bf16 v[6:9], v[188:191], v[230:233], v[6:9]
	v_mfma_f32_16x16x32_bf16 v[2:5], v[198:201], v[230:233], v[2:5]
	v_mfma_f32_16x16x32_bf16 v[54:57], v[192:195], v[210:213], v[54:57]
	v_mfma_f32_16x16x32_bf16 v[50:53], v[202:205], v[210:213], v[50:53]
	v_mfma_f32_16x16x32_bf16 v[38:41], v[192:195], v[218:221], v[38:41]
	v_mfma_f32_16x16x32_bf16 v[34:37], v[202:205], v[218:221], v[34:37]
	v_mfma_f32_16x16x32_bf16 v[22:25], v[192:195], v[226:229], v[22:25]
	v_mfma_f32_16x16x32_bf16 v[18:21], v[202:205], v[226:229], v[18:21]
	v_mfma_f32_16x16x32_bf16 v[6:9], v[192:195], v[234:237], v[6:9]
	v_mfma_f32_16x16x32_bf16 v[2:5], v[202:205], v[234:237], v[2:5]
	s_setprio 0
	s_barrier
	s_add_i32 s82, s82, 2
	s_add_u32 s2, s2, 0x100
	s_addc_u32 s3, s3, 0
	s_add_u32 s80, s80, 0x100
	s_addc_u32 s81, s81, 0
	s_cmp_gt_u32 s82, 61

; #define PG8_STAGE(bufoff, gbase, voff) do { _Pragma("unroll") for (int _i = 0; _i < 2; ++_i) \
;         __builtin_amdgcn_global_load_lds((const unsigned*)((const char*)(gbase) + (voff)[_i]), (PG8_LAS unsigned*)(lds + (bufoff) + ldsw + _i * 8192), 16, 0, 0); } while (0)
; #define PG8_LDA(dst, b, h) do { _Pragma("unroll") for (int m = 0; m < 4; ++m) _Pragma("unroll") for (int k = 0; k < 2; ++k) dst[m][k] = *(const PG8_LAS bf16x8*)(lds + PG8_SA(b, h) + aoff + m * 2048 + k * 1024); } while (0)
; #define PG8_LDB(dst, b, h) do { _Pragma("unroll") for (int n = 0; n < 2; ++n) _Pragma("unroll") for (int k = 0; k < 2; ++k) dst[n][k] = *(const PG8_LAS bf16x8*)(lds + PG8_SB(b, h) + boff + n * 2048 + k * 1024); } while (0)
; template <class Epi, class Sched, bool ALIGN_EPI = false, bool SP2 = false>
; __device__ __forceinline__ void gemm_phase(PG8_LAS unsigned char* lds, const Gemm g, const Sched& S, const Epi& E) {
;     ...
;         const bool has_next = S.next(ui + 1, nxt);
;         const char* nA = has_next ? (const char*)g.A + (size_t)nxt.pm * tstep : cA; const char* nB = has_next ? (const char*)g.Bt + (size_t)nxt.pn * tstep : cB;
;         for (int t = 0; t < nt; t += 2) {
;             const bool last = (t == nt - 2);
;             const char* a1 = cA + (size_t)(t + 1) * kstep;
;             const char* a2 = last ? nA : cA + (size_t)(t + 2) * kstep; const char* b2 = last ? nB : cB + (size_t)(t + 2) * kstep;
;             const char* a3 = a2 + kstep; const char* b3 = b2 + kstep;
;             if (last && has_next) S.a_ready(nxt);
;             if constexpr (SP2) {
;             PG8_LDB(B0, 0, 0); PG8_LDB(B1, 0, 1); PG8_SCHED; PG8_LDA(At, 0, 0); PG8_STAGE(PG8_SA(1, 1), a1 + hstep, voffA);
;             PG8_WAIT_V(8); PG8_WAIT_L(0); PG8_BAR; PG8_MMA(0, 0, At, B0); PG8_MMA(0, 1, At, B1); PG8_BAR; PG8_SCHED;
;             PG8_LDA(At, 0, 1); PG8_STAGE(PG8_SB(0, 0), b2, voffB); PG8_STAGE(PG8_SB(0, 1), b2 + hstep, voffB); PG8_STAGE(PG8_SA(0, 0), a2, voffA);
;             PG8_WAIT_V(8); PG8_WAIT_L(0); PG8_BAR; PG8_MMA(1, 0, At, B0); PG8_MMA(1, 1, At, B1); PG8_BAR; PG8_SCHED;
;     ...
; #pragma unroll
;         for (int a = 0; a < 2; ++a)
; #pragma unroll
;             for (int b = 0; b < 2; ++b)
; #pragma unroll
;                 for (int m = 0; m < 4; ++m)
; #pragma unroll
;                     for (int n = 0; n < 2; ++n) acc[a][b][m][n] = (f32x4){0.f, 0.f, 0.f, 0.f};
.LBB0_216:
	s_ashr_i32 s35, s34, 31
	s_lshl_b64 s[38:39], s[34:35], 21
	s_add_u32 s38, s51, s38
	s_addc_u32 s39, s52, s39
	s_and_b64 s[40:41], s[36:37], exec
	s_cselect_b32 s3, s39, s45
	s_cselect_b32 s35, s38, s44
	s_ashr_i32 s17, s16, 31
	s_lshl_b64 s[40:41], s[16:17], 21
	s_add_u32 s40, s53, s40
	s_addc_u32 s41, s54, s41
	s_and_b64 s[48:49], s[36:37], exec
	s_cselect_b32 s17, s41, s47
	s_cselect_b32 s43, s40, s46
	s_add_u32 s44, s44, 0x100080
	s_addc_u32 s45, s45, 0
	s_add_u32 s78, s46, 0x100
	s_addc_u32 s79, s47, 0
	s_mov_b32 s80, -2
	ds_read_b128 v[152:155], v159
	ds_read_b128 v[168:171], v159 offset:1024
	ds_read_b128 v[172:175], v159 offset:2048
	ds_read_b128 v[176:179], v159 offset:3072
	ds_read_b128 v[180:183], v160
	ds_read_b128 v[184:187], v160 offset:1024
	ds_read_b128 v[188:191], v160 offset:2048
	ds_read_b128 v[192:195], v160 offset:3072
	s_add_u32 s46, s44, 0xfff00080
	s_addc_u32 s47, s45, -1
	s_cmp_eq_u32 s80, 60
	s_cselect_b32 s49, s3, s47
	s_cselect_b32 s48, s35, s46
	s_cselect_b32 s47, s17, s79
	s_cselect_b32 s46, s43, s78
	v_lshl_add_u64 v[156:157], s[44:45], 0, v[144:145]
	s_add_i32 m0, s56, 0xc000
	ds_read_b128 v[198:201], v161
	ds_read_b128 v[202:205], v161 offset:1024
	ds_read_b128 v[206:209], v161 offset:2048
	ds_read_b128 v[210:213], v161 offset:3072
	ds_read_b128 v[214:217], v161 offset:4096
	ds_read_b128 v[218:221], v161 offset:5120
	ds_read_b128 v[222:225], v161 offset:6144
	ds_read_b128 v[226:229], v161 offset:7168
	global_load_lds_dwordx4 v[156:157], off
	v_lshl_add_u64 v[156:157], s[44:45], 0, v[146:147]
	s_add_i32 m0, s56, 0xe000
	s_nop 0
	global_load_lds_dwordx4 v[156:157], off
	s_waitcnt vmcnt(8)
	s_waitcnt lgkmcnt(0)
	s_setprio 1
	s_barrier
	v_mfma_f32_16x16x32_bf16 v[126:129], v[152:155], v[198:201], 0
	v_mfma_f32_16x16x32_bf16 v[122:125], v[172:175], v[198:201], 0
	v_mfma_f32_16x16x32_bf16 v[110:113], v[152:155], v[206:209], 0
	v_mfma_f32_16x16x32_bf16 v[106:109], v[172:175], v[206:209], 0
	v_mfma_f32_16x16x32_bf16 v[94:97], v[152:155], v[214:217], 0
	v_mfma_f32_16x16x32_bf16 v[90:93], v[172:175], v[214:217], 0
	v_mfma_f32_16x16x32_bf16 v[78:81], v[152:155], v[222:225], 0
	v_mfma_f32_16x16x32_bf16 v[74:77], v[172:175], v[222:225], 0
	v_mfma_f32_16x16x32_bf16 v[126:129], v[168:171], v[202:205], v[126:129]
	v_mfma_f32_16x16x32_bf16 v[122:125], v[176:179], v[202:205], v[122:125]
	v_mfma_f32_16x16x32_bf16 v[110:113], v[168:171], v[210:213], v[110:113]
	v_mfma_f32_16x16x32_bf16 v[106:109], v[176:179], v[210:213], v[106:109]
	v_mfma_f32_16x16x32_bf16 v[94:97], v[168:171], v[218:221], v[94:97]
	v_mfma_f32_16x16x32_bf16 v[90:93], v[176:179], v[218:221], v[90:93]
	v_mfma_f32_16x16x32_bf16 v[78:81], v[168:171], v[226:229], v[78:81]
	v_mfma_f32_16x16x32_bf16 v[74:77], v[176:179], v[226:229], v[74:77]
	s_setprio 0
	s_setprio 1
	v_mfma_f32_16x16x32_bf16 v[118:121], v[180:183], v[198:201], 0
	v_mfma_f32_16x16x32_bf16 v[114:117], v[188:191], v[198:201], 0
	v_mfma_f32_16x16x32_bf16 v[102:105], v[180:183], v[206:209], 0
	v_mfma_f32_16x16x32_bf16 v[98:101], v[188:191], v[206:209], 0
	v_mfma_f32_16x16x32_bf16 v[86:89], v[180:183], v[214:217], 0
	v_mfma_f32_16x16x32_bf16 v[82:85], v[188:191], v[214:217], 0
	v_mfma_f32_16x16x32_bf16 v[70:73], v[180:183], v[222:225], 0
	v_mfma_f32_16x16x32_bf16 v[66:69], v[188:191], v[222:225], 0
	v_mfma_f32_16x16x32_bf16 v[118:121], v[184:187], v[202:205], v[118:121]
	v_mfma_f32_16x16x32_bf16 v[114:117], v[192:195], v[202:205], v[114:117]
	v_mfma_f32_16x16x32_bf16 v[102:105], v[184:187], v[210:213], v[102:105]
	v_mfma_f32_16x16x32_bf16 v[98:101], v[192:195], v[210:213], v[98:101]
	v_mfma_f32_16x16x32_bf16 v[86:89], v[184:187], v[218:221], v[86:89]
	v_mfma_f32_16x16x32_bf16 v[82:85], v[192:195], v[218:221], v[82:85]
	v_mfma_f32_16x16x32_bf16 v[70:73], v[184:187], v[226:229], v[70:73]
	v_mfma_f32_16x16x32_bf16 v[66:69], v[192:195], v[226:229], v[66:69]
	s_setprio 0
	s_barrier
	s_add_i32 s81, s73, s55
	v_lshl_add_u64 v[156:157], s[46:47], 0, v[132:133]
	s_mov_b32 m0, s81
	ds_read_b128 v[198:201], v161 offset:16384
	ds_read_b128 v[202:205], v161 offset:17408
	ds_read_b128 v[206:209], v161 offset:18432
	ds_read_b128 v[210:213], v161 offset:19456
	ds_read_b128 v[214:217], v161 offset:20480
	ds_read_b128 v[218:221], v161 offset:21504
	ds_read_b128 v[222:225], v161 offset:22528
	ds_read_b128 v[226:229], v161 offset:23552
	global_load_lds_dwordx4 v[156:157], off
	s_add_i32 m0, s81, 0x2000
	s_add_u32 s82, s46, 0x100000
	v_lshl_add_u64 v[230:231], s[46:47], 0, v[136:137]
	s_addc_u32 s83, s47, 0
	s_add_i32 s81, s74, s55
	global_load_lds_dwordx4 v[230:231], off
	v_lshl_add_u64 v[232:233], s[82:83], 0, v[132:133]
	s_mov_b32 m0, s81
	v_lshl_add_u64 v[234:235], s[48:49], 0, v[134:135]
	global_load_lds_dwordx4 v[232:233], off
	v_lshl_add_u64 v[232:233], s[82:83], 0, v[136:137]
	s_add_i32 m0, s81, 0x2000
	s_nop 0
	global_load_lds_dwordx4 v[232:233], off
	v_lshl_add_u64 v[232:233], s[48:49], 0, v[130:131]
	s_mov_b32 m0, s56
	s_nop 0
	global_load_lds_dwordx4 v[232:233], off
	s_mov_b32 m0, s57
	s_nop 0
	global_load_lds_dwordx4 v[234:235], off
	s_waitcnt vmcnt(8)
	s_waitcnt lgkmcnt(0)
	s_setprio 1
	s_barrier
; #define PG8_STAGE(bufoff, gbase, voff) do { _Pragma("unroll") for (int _i = 0; _i < 2; ++_i) \
;         __builtin_amdgcn_global_load_lds((const unsigned*)((const char*)(gbase) + (voff)[_i]), (PG8_LAS unsigned*)(lds + (bufoff) + ldsw + _i * 8192), 16, 0, 0); } while (0)
; #define PG8_LDA(dst, b, h) do { _Pragma("unroll") for (int m = 0; m < 4; ++m) _Pragma("unroll") for (int k = 0; k < 2; ++k) dst[m][k] = *(const PG8_LAS bf16x8*)(lds + PG8_SA(b, h) + aoff + m * 2048 + k * 1024); } while (0)
; #define PG8_LDB(dst, b, h) do { _Pragma("unroll") for (int n = 0; n < 2; ++n) _Pragma("unroll") for (int k = 0; k < 2; ++k) dst[n][k] = *(const PG8_LAS bf16x8*)(lds + PG8_SB(b, h) + boff + n * 2048 + k * 1024); } while (0)
; #define PG8_MMA(ai, bj, At, Bt) do { __builtin_amdgcn_s_setprio(1); _Pragma("unroll") for (int m = 0; m < 4; ++m) _Pragma("unroll") for (int n = 0; n < 2; ++n) _Pragma("unroll") for (int k = 0; k < 2; ++k) \
;         acc[ai][bj][m][n] = __builtin_amdgcn_mfma_f32_16x16x32_bf16(Bt[n][k], At[m][k], acc[ai][bj][m][n], 0, 0, 0); __builtin_amdgcn_s_setprio(0); } while (0)
; #define PG8_WAIT_V(n) asm volatile("s_waitcnt vmcnt(" #n ")" ::: "memory")
; #define PG8_WAIT_L(n) asm volatile("s_waitcnt lgkmcnt(" #n ")" ::: "memory")
; #define PG8_BAR __builtin_amdgcn_s_barrier()
; #define PG8_SCHED __builtin_amdgcn_sched_barrier(0)
; template <class Epi, class Sched, bool ALIGN_EPI = false, bool SP2 = false>
; __device__ __forceinline__ void gemm_phase(PG8_LAS unsigned char* lds, const Gemm g, const Sched& S, const Epi& E) {
;     ...
;             PG8_WAIT_V(8); PG8_WAIT_L(0); PG8_BAR; PG8_MMA(0, 0, At, B0); PG8_MMA(0, 1, At, B1); PG8_BAR; PG8_SCHED;
;             PG8_LDA(At, 0, 1); PG8_STAGE(PG8_SB(0, 0), b2, voffB); PG8_STAGE(PG8_SB(0, 1), b2 + hstep, voffB); PG8_STAGE(PG8_SA(0, 0), a2, voffA);
;             PG8_WAIT_V(8); PG8_WAIT_L(0); PG8_BAR; PG8_MMA(1, 0, At, B0); PG8_MMA(1, 1, At, B1); PG8_BAR; PG8_SCHED;
;             PG8_LDB(B0, 1, 0); PG8_LDB(B1, 1, 1); PG8_SCHED; PG8_LDA(At, 1, 0); PG8_STAGE(PG8_SA(0, 1), a2 + hstep, voffA);
;             PG8_WAIT_V(8); PG8_WAIT_L(0); PG8_BAR; PG8_MMA(0, 0, At, B0); PG8_MMA(0, 1, At, B1); PG8_BAR; PG8_SCHED;
;             PG8_LDA(At, 1, 1); PG8_STAGE(PG8_SB(1, 0), b3, voffB); PG8_STAGE(PG8_SB(1, 1), b3 + hstep, voffB); PG8_STAGE(PG8_SA(1, 0), a3, voffA);
	v_mfma_f32_16x16x32_bf16 v[62:65], v[152:155], v[198:201], 0
	v_mfma_f32_16x16x32_bf16 v[58:61], v[172:175], v[198:201], 0
	v_mfma_f32_16x16x32_bf16 v[46:49], v[152:155], v[206:209], 0
	v_mfma_f32_16x16x32_bf16 v[42:45], v[172:175], v[206:209], 0
	v_mfma_f32_16x16x32_bf16 v[30:33], v[152:155], v[214:217], 0
	v_mfma_f32_16x16x32_bf16 v[26:29], v[172:175], v[214:217], 0
	v_mfma_f32_16x16x32_bf16 v[14:17], v[152:155], v[222:225], 0
	v_mfma_f32_16x16x32_bf16 v[10:13], v[172:175], v[222:225], 0
	v_mfma_f32_16x16x32_bf16 v[62:65], v[168:171], v[202:205], v[62:65]
	v_mfma_f32_16x16x32_bf16 v[58:61], v[176:179], v[202:205], v[58:61]
	v_mfma_f32_16x16x32_bf16 v[46:49], v[168:171], v[210:213], v[46:49]
	v_mfma_f32_16x16x32_bf16 v[42:45], v[176:179], v[210:213], v[42:45]
	v_mfma_f32_16x16x32_bf16 v[30:33], v[168:171], v[218:221], v[30:33]
	v_mfma_f32_16x16x32_bf16 v[26:29], v[176:179], v[218:221], v[26:29]
	v_mfma_f32_16x16x32_bf16 v[14:17], v[168:171], v[226:229], v[14:17]
	v_mfma_f32_16x16x32_bf16 v[10:13], v[176:179], v[226:229], v[10:13]
	s_setprio 0
	s_setprio 1
	v_mfma_f32_16x16x32_bf16 v[54:57], v[180:183], v[198:201], 0
	v_mfma_f32_16x16x32_bf16 v[50:53], v[188:191], v[198:201], 0
	v_mfma_f32_16x16x32_bf16 v[38:41], v[180:183], v[206:209], 0
	v_mfma_f32_16x16x32_bf16 v[34:37], v[188:191], v[206:209], 0
	v_mfma_f32_16x16x32_bf16 v[22:25], v[180:183], v[214:217], 0
	v_mfma_f32_16x16x32_bf16 v[18:21], v[188:191], v[214:217], 0
	v_mfma_f32_16x16x32_bf16 v[6:9], v[180:183], v[222:225], 0
	v_mfma_f32_16x16x32_bf16 v[2:5], v[188:191], v[222:225], 0
	v_mfma_f32_16x16x32_bf16 v[54:57], v[184:187], v[202:205], v[54:57]
	v_mfma_f32_16x16x32_bf16 v[50:53], v[192:195], v[202:205], v[50:53]
	v_mfma_f32_16x16x32_bf16 v[38:41], v[184:187], v[210:213], v[38:41]
	v_mfma_f32_16x16x32_bf16 v[34:37], v[192:195], v[210:213], v[34:37]
	v_mfma_f32_16x16x32_bf16 v[22:25], v[184:187], v[218:221], v[22:25]
	v_mfma_f32_16x16x32_bf16 v[18:21], v[192:195], v[218:221], v[18:21]
	v_mfma_f32_16x16x32_bf16 v[6:9], v[184:187], v[226:229], v[6:9]
	v_mfma_f32_16x16x32_bf16 v[2:5], v[192:195], v[226:229], v[2:5]
	s_setprio 0
	s_barrier
	s_add_i32 s81, 0, 0x18000
	v_add_u32_e32 v149, s81, v164
	s_add_i32 s82, 0, 0x1c000
	ds_read_b128 v[152:155], v149
	ds_read_b128 v[168:171], v149 offset:1024
	ds_read_b128 v[172:175], v149 offset:2048
	ds_read_b128 v[176:179], v149 offset:3072
	v_add_u32_e32 v149, s82, v164
	ds_read_b128 v[180:183], v149
	ds_read_b128 v[184:187], v149 offset:1024
	ds_read_b128 v[188:191], v149 offset:2048
	ds_read_b128 v[192:195], v149 offset:3072
	s_add_u32 s48, s48, 0x100000
	s_addc_u32 s49, s49, 0
	s_mov_b32 m0, s58
	v_lshl_add_u64 v[236:237], s[48:49], 0, v[130:131]
	ds_read_b128 v[198:201], v161 offset:32768
	ds_read_b128 v[202:205], v161 offset:33792
	ds_read_b128 v[206:209], v161 offset:34816
	ds_read_b128 v[210:213], v161 offset:35840
	ds_read_b128 v[214:217], v161 offset:36864
	ds_read_b128 v[218:221], v161 offset:37888
	ds_read_b128 v[222:225], v161 offset:38912
	ds_read_b128 v[226:229], v161 offset:39936
	global_load_lds_dwordx4 v[236:237], off
	v_lshl_add_u64 v[236:237], s[48:49], 0, v[134:135]
	s_mov_b32 m0, s59
	s_nop 0
	global_load_lds_dwordx4 v[236:237], off
	s_waitcnt vmcnt(8)
	s_waitcnt lgkmcnt(0)
	s_setprio 1
	s_barrier
	v_mfma_f32_16x16x32_bf16 v[126:129], v[152:155], v[198:201], v[126:129]
	v_mfma_f32_16x16x32_bf16 v[122:125], v[172:175], v[198:201], v[122:125]
	v_mfma_f32_16x16x32_bf16 v[110:113], v[152:155], v[206:209], v[110:113]
	v_mfma_f32_16x16x32_bf16 v[106:109], v[172:175], v[206:209], v[106:109]
	v_mfma_f32_16x16x32_bf16 v[94:97], v[152:155], v[214:217], v[94:97]
	v_mfma_f32_16x16x32_bf16 v[90:93], v[172:175], v[214:217], v[90:93]
	v_mfma_f32_16x16x32_bf16 v[78:81], v[152:155], v[222:225], v[78:81]
	v_mfma_f32_16x16x32_bf16 v[74:77], v[172:175], v[222:225], v[74:77]
	v_mfma_f32_16x16x32_bf16 v[126:129], v[168:171], v[202:205], v[126:129]
	v_mfma_f32_16x16x32_bf16 v[122:125], v[176:179], v[202:205], v[122:125]
	v_mfma_f32_16x16x32_bf16 v[110:113], v[168:171], v[210:213], v[110:113]
	v_mfma_f32_16x16x32_bf16 v[106:109], v[176:179], v[210:213], v[106:109]
	v_mfma_f32_16x16x32_bf16 v[94:97], v[168:171], v[218:221], v[94:97]
	v_mfma_f32_16x16x32_bf16 v[90:93], v[176:179], v[218:221], v[90:93]
	v_mfma_f32_16x16x32_bf16 v[78:81], v[168:171], v[226:229], v[78:81]
	v_mfma_f32_16x16x32_bf16 v[74:77], v[176:179], v[226:229], v[74:77]
	s_setprio 0
	s_setprio 1
	v_mfma_f32_16x16x32_bf16 v[118:121], v[180:183], v[198:201], v[118:121]
	v_mfma_f32_16x16x32_bf16 v[114:117], v[188:191], v[198:201], v[114:117]
	v_mfma_f32_16x16x32_bf16 v[102:105], v[180:183], v[206:209], v[102:105]
	v_mfma_f32_16x16x32_bf16 v[98:101], v[188:191], v[206:209], v[98:101]
	v_mfma_f32_16x16x32_bf16 v[86:89], v[180:183], v[214:217], v[86:89]
	v_mfma_f32_16x16x32_bf16 v[82:85], v[188:191], v[214:217], v[82:85]
	v_mfma_f32_16x16x32_bf16 v[70:73], v[180:183], v[222:225], v[70:73]
	v_mfma_f32_16x16x32_bf16 v[66:69], v[188:191], v[222:225], v[66:69]
	v_mfma_f32_16x16x32_bf16 v[118:121], v[184:187], v[202:205], v[118:121]
	v_mfma_f32_16x16x32_bf16 v[114:117], v[192:195], v[202:205], v[114:117]
	v_mfma_f32_16x16x32_bf16 v[102:105], v[184:187], v[210:213], v[102:105]
	v_mfma_f32_16x16x32_bf16 v[98:101], v[192:195], v[210:213], v[98:101]
	v_mfma_f32_16x16x32_bf16 v[86:89], v[184:187], v[218:221], v[86:89]
	v_mfma_f32_16x16x32_bf16 v[82:85], v[192:195], v[218:221], v[82:85]
	v_mfma_f32_16x16x32_bf16 v[70:73], v[184:187], v[226:229], v[70:73]
	v_mfma_f32_16x16x32_bf16 v[66:69], v[192:195], v[226:229], v[66:69]
	s_setprio 0
	s_barrier
; #define PG8_STAGE(bufoff, gbase, voff) do { _Pragma("unroll") for (int _i = 0; _i < 2; ++_i) \
;         __builtin_amdgcn_global_load_lds((const unsigned*)((const char*)(gbase) + (voff)[_i]), (PG8_LAS unsigned*)(lds + (bufoff) + ldsw + _i * 8192), 16, 0, 0); } while (0)
; #define PG8_LDA(dst, b, h) do { _Pragma("unroll") for (int m = 0; m < 4; ++m) _Pragma("unroll") for (int k = 0; k < 2; ++k) dst[m][k] = *(const PG8_LAS bf16x8*)(lds + PG8_SA(b, h) + aoff + m * 2048 + k * 1024); } while (0)
; #define PG8_LDB(dst, b, h) do { _Pragma("unroll") for (int n = 0; n < 2; ++n) _Pragma("unroll") for (int k = 0; k < 2; ++k) dst[n][k] = *(const PG8_LAS bf16x8*)(lds + PG8_SB(b, h) + boff + n * 2048 + k * 1024); } while (0)
; template <class Epi, class Sched, bool ALIGN_EPI = false, bool SP2 = false>
; __device__ __forceinline__ void gemm_phase(PG8_LAS unsigned char* lds, const Gemm g, const Sched& S, const Epi& E) {
;     ...
;         for (int t = 0; t < nt; t += 2) {
;             const bool last = (t == nt - 2);
;             const char* a1 = cA + (size_t)(t + 1) * kstep;
;             const char* a2 = last ? nA : cA + (size_t)(t + 2) * kstep; const char* b2 = last ? nB : cB + (size_t)(t + 2) * kstep;
;             const char* a3 = a2 + kstep; const char* b3 = b2 + kstep;
;             if (last && has_next) S.a_ready(nxt);
;             if constexpr (SP2) {
;             PG8_LDB(B0, 0, 0); PG8_LDB(B1, 0, 1); PG8_SCHED; PG8_LDA(At, 0, 0); PG8_STAGE(PG8_SA(1, 1), a1 + hstep, voffA);
;             PG8_WAIT_V(8); PG8_WAIT_L(0); PG8_BAR; PG8_MMA(0, 0, At, B0); PG8_MMA(0, 1, At, B1); PG8_BAR; PG8_SCHED;
;             PG8_LDA(At, 0, 1); PG8_STAGE(PG8_SB(0, 0), b2, voffB); PG8_STAGE(PG8_SB(0, 1), b2 + hstep, voffB); PG8_STAGE(PG8_SA(0, 0), a2, voffA);
;             PG8_WAIT_V(8); PG8_WAIT_L(0); PG8_BAR; PG8_MMA(1, 0, At, B0); PG8_MMA(1, 1, At, B1); PG8_BAR; PG8_SCHED;
;             PG8_LDB(B0, 1, 0); PG8_LDB(B1, 1, 1); PG8_SCHED; PG8_LDA(At, 1, 0); PG8_STAGE(PG8_SA(0, 1), a2 + hstep, voffA);
;             PG8_WAIT_V(8); PG8_WAIT_L(0); PG8_BAR; PG8_MMA(0, 0, At, B0); PG8_MMA(0, 1, At, B1); PG8_BAR; PG8_SCHED;
;             PG8_LDA(At, 1, 1); PG8_STAGE(PG8_SB(1, 0), b3, voffB); PG8_STAGE(PG8_SB(1, 1), b3 + hstep, voffB); PG8_STAGE(PG8_SA(1, 0), a3, voffA);
;             PG8_WAIT_V(8); PG8_WAIT_L(0); PG8_BAR; PG8_MMA(1, 0, At, B0); PG8_MMA(1, 1, At, B1); PG8_BAR; PG8_SCHED;
	s_add_i32 s48, s81, s55
	v_lshl_add_u64 v[156:157], v[156:157], 0, s[10:11]
	s_mov_b32 m0, s48
	ds_read_b128 v[198:201], v161 offset:49152
	ds_read_b128 v[202:205], v161 offset:50176
	ds_read_b128 v[206:209], v161 offset:51200
	ds_read_b128 v[210:213], v161 offset:52224
	ds_read_b128 v[214:217], v161 offset:53248
	ds_read_b128 v[218:221], v161 offset:54272
	ds_read_b128 v[222:225], v161 offset:55296
	ds_read_b128 v[226:229], v161 offset:56320
	global_load_lds_dwordx4 v[156:157], off
	s_add_i32 m0, s48, 0x2000
	s_add_u32 s46, s46, 0x100080
	v_lshl_add_u64 v[156:157], v[230:231], 0, s[10:11]
	s_addc_u32 s47, s47, 0
	s_add_i32 s48, s82, s55
	global_load_lds_dwordx4 v[156:157], off
	v_lshl_add_u64 v[156:157], s[46:47], 0, v[132:133]
	s_mov_b32 m0, s48
	s_nop 0
	global_load_lds_dwordx4 v[156:157], off
	v_lshl_add_u64 v[156:157], s[46:47], 0, v[136:137]
	s_add_i32 m0, s48, 0x2000
	s_nop 0
	global_load_lds_dwordx4 v[156:157], off
	v_lshl_add_u64 v[156:157], v[232:233], 0, s[10:11]
	s_mov_b32 m0, s70
	s_nop 0
	global_load_lds_dwordx4 v[156:157], off
	v_lshl_add_u64 v[156:157], v[234:235], 0, s[10:11]
	s_mov_b32 m0, s71
	s_nop 0
	global_load_lds_dwordx4 v[156:157], off
	s_waitcnt vmcnt(8)
	s_waitcnt lgkmcnt(0)
	s_setprio 1
	s_barrier
	v_mfma_f32_16x16x32_bf16 v[62:65], v[152:155], v[198:201], v[62:65]
	v_mfma_f32_16x16x32_bf16 v[58:61], v[172:175], v[198:201], v[58:61]
	v_mfma_f32_16x16x32_bf16 v[46:49], v[152:155], v[206:209], v[46:49]
	v_mfma_f32_16x16x32_bf16 v[42:45], v[172:175], v[206:209], v[42:45]
	v_mfma_f32_16x16x32_bf16 v[30:33], v[152:155], v[214:217], v[30:33]
	v_mfma_f32_16x16x32_bf16 v[26:29], v[172:175], v[214:217], v[26:29]
	v_mfma_f32_16x16x32_bf16 v[14:17], v[152:155], v[222:225], v[14:17]
	v_mfma_f32_16x16x32_bf16 v[10:13], v[172:175], v[222:225], v[10:13]
	v_mfma_f32_16x16x32_bf16 v[62:65], v[168:171], v[202:205], v[62:65]
	v_mfma_f32_16x16x32_bf16 v[58:61], v[176:179], v[202:205], v[58:61]
	v_mfma_f32_16x16x32_bf16 v[46:49], v[168:171], v[210:213], v[46:49]
	v_mfma_f32_16x16x32_bf16 v[42:45], v[176:179], v[210:213], v[42:45]
	v_mfma_f32_16x16x32_bf16 v[30:33], v[168:171], v[218:221], v[30:33]
	v_mfma_f32_16x16x32_bf16 v[26:29], v[176:179], v[218:221], v[26:29]
	v_mfma_f32_16x16x32_bf16 v[14:17], v[168:171], v[226:229], v[14:17]
	v_mfma_f32_16x16x32_bf16 v[10:13], v[176:179], v[226:229], v[10:13]
	s_setprio 0
	s_setprio 1
	v_mfma_f32_16x16x32_bf16 v[54:57], v[180:183], v[198:201], v[54:57]
	v_mfma_f32_16x16x32_bf16 v[50:53], v[188:191], v[198:201], v[50:53]
	v_mfma_f32_16x16x32_bf16 v[38:41], v[180:183], v[206:209], v[38:41]
	v_mfma_f32_16x16x32_bf16 v[34:37], v[188:191], v[206:209], v[34:37]
	v_mfma_f32_16x16x32_bf16 v[22:25], v[180:183], v[214:217], v[22:25]
	v_mfma_f32_16x16x32_bf16 v[18:21], v[188:191], v[214:217], v[18:21]
	v_mfma_f32_16x16x32_bf16 v[6:9], v[180:183], v[222:225], v[6:9]
	v_mfma_f32_16x16x32_bf16 v[2:5], v[188:191], v[222:225], v[2:5]
	v_mfma_f32_16x16x32_bf16 v[54:57], v[184:187], v[202:205], v[54:57]
	v_mfma_f32_16x16x32_bf16 v[50:53], v[192:195], v[202:205], v[50:53]
	v_mfma_f32_16x16x32_bf16 v[38:41], v[184:187], v[210:213], v[38:41]
	v_mfma_f32_16x16x32_bf16 v[34:37], v[192:195], v[210:213], v[34:37]
	v_mfma_f32_16x16x32_bf16 v[22:25], v[184:187], v[218:221], v[22:25]
	v_mfma_f32_16x16x32_bf16 v[18:21], v[192:195], v[218:221], v[18:21]
	v_mfma_f32_16x16x32_bf16 v[6:9], v[184:187], v[226:229], v[6:9]
	v_mfma_f32_16x16x32_bf16 v[2:5], v[192:195], v[226:229], v[2:5]
	s_setprio 0
	s_barrier
	s_add_i32 s80, s80, 2
	s_add_u32 s44, s44, 0x100
	s_addc_u32 s45, s45, 0
	s_add_u32 s78, s78, 0x100
	s_addc_u32 s79, s79, 0
	s_cmp_gt_u32 s80, 61

; #define PG8_STAGE(bufoff, gbase, voff) do { _Pragma("unroll") for (int _i = 0; _i < 2; ++_i) \
;         __builtin_amdgcn_global_load_lds((const unsigned*)((const char*)(gbase) + (voff)[_i]), (PG8_LAS unsigned*)(lds + (bufoff) + ldsw + _i * 8192), 16, 0, 0); } while (0)
; #define PG8_LDA(dst, b, h) do { _Pragma("unroll") for (int m = 0; m < 4; ++m) _Pragma("unroll") for (int k = 0; k < 2; ++k) dst[m][k] = *(const PG8_LAS bf16x8*)(lds + PG8_SA(b, h) + aoff + m * 2048 + k * 1024); } while (0)
; #define PG8_WAIT_V(n) asm volatile("s_waitcnt vmcnt(" #n ")" ::: "memory")
; #define PG8_WAIT_L(n) asm volatile("s_waitcnt lgkmcnt(" #n ")" ::: "memory")
; template <class Epi, class Sched, bool ALIGN_EPI = false, bool SP2 = false>
; __device__ __forceinline__ void gemm_phase(PG8_LAS unsigned char* lds, const Gemm g, const Sched& S, const Epi& E) {
;     ...
;         const bool has_next = S.next(ui + 1, nxt);
;         const char* nA = has_next ? (const char*)g.A + (size_t)nxt.pm * tstep : cA; const char* nB = has_next ? (const char*)g.Bt + (size_t)nxt.pn * tstep : cB;
;         for (int t = 0; t < nt; t += 2) {
;             const bool last = (t == nt - 2);
;             const char* a1 = cA + (size_t)(t + 1) * kstep;
;             const char* a2 = last ? nA : cA + (size_t)(t + 2) * kstep; const char* b2 = last ? nB : cB + (size_t)(t + 2) * kstep;
;             const char* a3 = a2 + kstep; const char* b3 = b2 + kstep;
;             if (last && has_next) S.a_ready(nxt);
;             if constexpr (SP2) {
;             PG8_LDB(B0, 0, 0); PG8_LDB(B1, 0, 1); PG8_SCHED; PG8_LDA(At, 0, 0); PG8_STAGE(PG8_SA(1, 1), a1 + hstep, voffA);
;             PG8_WAIT_V(8); PG8_WAIT_L(0); PG8_BAR; PG8_MMA(0, 0, At, B0); PG8_MMA(0, 1, At, B1); PG8_BAR; PG8_SCHED;
;             PG8_LDA(At, 0, 1); PG8_STAGE(PG8_SB(0, 0), b2, voffB); PG8_STAGE(PG8_SB(0, 1), b2 + hstep, voffB); PG8_STAGE(PG8_SA(0, 0), a2, voffA);
;             PG8_WAIT_V(8); PG8_WAIT_L(0); PG8_BAR; PG8_MMA(1, 0, At, B0); PG8_MMA(1, 1, At, B1); PG8_BAR; PG8_SCHED;
;     ...
; #pragma unroll
;         for (int a = 0; a < 2; ++a)
; #pragma unroll
;             for (int b = 0; b < 2; ++b)
; #pragma unroll
;                 for (int m = 0; m < 4; ++m)
; #pragma unroll
;                     for (int n = 0; n < 2; ++n) acc[a][b][m][n] = (f32x4){0.f, 0.f, 0.f, 0.f};
;         cur = nxt; cA = nA; cB = nB; ++ui;
.LBB0_709:
	s_ashr_i32 s43, s42, 31
	s_lshl_b64 s[44:45], s[42:43], 21
	s_add_u32 s44, s19, s44
	s_addc_u32 s45, s21, s45
	s_and_b64 s[46:47], s[4:5], exec
	s_cselect_b32 s43, s45, s49
	s_cselect_b32 s72, s44, s48
	s_ashr_i32 s41, s40, 31
	s_lshl_b64 s[46:47], s[40:41], 21
	s_add_u32 s46, s54, s46
	s_addc_u32 s47, s55, s47
	s_and_b64 s[52:53], s[4:5], exec
	s_cselect_b32 s41, s47, s51
	s_cselect_b32 s73, s46, s50
	s_add_u32 s48, s48, 0x100080
	s_addc_u32 s49, s49, 0
	s_add_u32 s74, s50, 0x100
	s_addc_u32 s75, s51, 0
	s_mov_b32 s76, -2
	s_waitcnt lgkmcnt(0)
	ds_read_b128 v[146:149], v160
	ds_read_b128 v[164:167], v160 offset:1024
	ds_read_b128 v[168:171], v160 offset:2048
	ds_read_b128 v[172:175], v160 offset:3072
	ds_read_b128 v[176:179], v161
	ds_read_b128 v[180:183], v161 offset:1024
	ds_read_b128 v[184:187], v161 offset:2048
	ds_read_b128 v[188:191], v161 offset:3072
	s_add_u32 s50, s48, 0xfff00080
	s_addc_u32 s51, s49, -1
	s_cmp_eq_u32 s76, 60
	s_cselect_b32 s53, s43, s51
	s_cselect_b32 s52, s72, s50
	s_cselect_b32 s51, s41, s75
	s_cselect_b32 s50, s73, s74
	v_lshl_add_u64 v[226:227], s[48:49], 0, v[138:139]
	s_add_i32 m0, s9, 0xc000
	ds_read_b128 v[192:195], v162
	ds_read_b128 v[198:201], v162 offset:1024
	ds_read_b128 v[202:205], v162 offset:2048
	ds_read_b128 v[206:209], v162 offset:3072
	ds_read_b128 v[210:213], v162 offset:4096
	ds_read_b128 v[214:217], v162 offset:5120
	ds_read_b128 v[218:221], v162 offset:6144
	ds_read_b128 v[222:225], v162 offset:7168
	global_load_lds_dwordx4 v[226:227], off
	v_lshl_add_u64 v[226:227], s[48:49], 0, v[140:141]
	s_add_i32 m0, s9, 0xe000
	s_nop 0
	global_load_lds_dwordx4 v[226:227], off
	s_waitcnt vmcnt(8)
	s_waitcnt lgkmcnt(0)
	s_setprio 1
	s_barrier
	v_mfma_f32_16x16x32_bf16 v[126:129], v[146:149], v[192:195], 0
	v_mfma_f32_16x16x32_bf16 v[122:125], v[168:171], v[192:195], 0
	v_mfma_f32_16x16x32_bf16 v[110:113], v[146:149], v[202:205], 0
	v_mfma_f32_16x16x32_bf16 v[106:109], v[168:171], v[202:205], 0
	v_mfma_f32_16x16x32_bf16 v[94:97], v[146:149], v[210:213], 0
	v_mfma_f32_16x16x32_bf16 v[90:93], v[168:171], v[210:213], 0
	v_mfma_f32_16x16x32_bf16 v[78:81], v[146:149], v[218:221], 0
	v_mfma_f32_16x16x32_bf16 v[74:77], v[168:171], v[218:221], 0
	v_mfma_f32_16x16x32_bf16 v[126:129], v[164:167], v[198:201], v[126:129]
	v_mfma_f32_16x16x32_bf16 v[122:125], v[172:175], v[198:201], v[122:125]
	v_mfma_f32_16x16x32_bf16 v[110:113], v[164:167], v[206:209], v[110:113]
	v_mfma_f32_16x16x32_bf16 v[106:109], v[172:175], v[206:209], v[106:109]
	v_mfma_f32_16x16x32_bf16 v[94:97], v[164:167], v[214:217], v[94:97]
	v_mfma_f32_16x16x32_bf16 v[90:93], v[172:175], v[214:217], v[90:93]
	v_mfma_f32_16x16x32_bf16 v[78:81], v[164:167], v[222:225], v[78:81]
	v_mfma_f32_16x16x32_bf16 v[74:77], v[172:175], v[222:225], v[74:77]
	s_setprio 0
	s_setprio 1
	v_mfma_f32_16x16x32_bf16 v[118:121], v[176:179], v[192:195], 0
	v_mfma_f32_16x16x32_bf16 v[114:117], v[184:187], v[192:195], 0
	v_mfma_f32_16x16x32_bf16 v[102:105], v[176:179], v[202:205], 0
	v_mfma_f32_16x16x32_bf16 v[98:101], v[184:187], v[202:205], 0
	v_mfma_f32_16x16x32_bf16 v[86:89], v[176:179], v[210:213], 0
	v_mfma_f32_16x16x32_bf16 v[82:85], v[184:187], v[210:213], 0
	v_mfma_f32_16x16x32_bf16 v[70:73], v[176:179], v[218:221], 0
	v_mfma_f32_16x16x32_bf16 v[66:69], v[184:187], v[218:221], 0
	v_mfma_f32_16x16x32_bf16 v[118:121], v[180:183], v[198:201], v[118:121]
	v_mfma_f32_16x16x32_bf16 v[114:117], v[188:191], v[198:201], v[114:117]
	v_mfma_f32_16x16x32_bf16 v[102:105], v[180:183], v[206:209], v[102:105]
	v_mfma_f32_16x16x32_bf16 v[98:101], v[188:191], v[206:209], v[98:101]
	v_mfma_f32_16x16x32_bf16 v[86:89], v[180:183], v[214:217], v[86:89]
	v_mfma_f32_16x16x32_bf16 v[82:85], v[188:191], v[214:217], v[82:85]
	v_mfma_f32_16x16x32_bf16 v[70:73], v[180:183], v[222:225], v[70:73]
	v_mfma_f32_16x16x32_bf16 v[66:69], v[188:191], v[222:225], v[66:69]
	s_setprio 0
	s_barrier
	s_add_i32 s77, s69, s56
	v_lshl_add_u64 v[226:227], s[50:51], 0, v[132:133]
	s_mov_b32 m0, s77
	ds_read_b128 v[192:195], v162 offset:16384
	ds_read_b128 v[198:201], v162 offset:17408
	ds_read_b128 v[202:205], v162 offset:18432
	ds_read_b128 v[206:209], v162 offset:19456
	ds_read_b128 v[210:213], v162 offset:20480
	ds_read_b128 v[214:217], v162 offset:21504
	ds_read_b128 v[218:221], v162 offset:22528
	ds_read_b128 v[222:225], v162 offset:23552
	global_load_lds_dwordx4 v[226:227], off
	s_add_i32 m0, s77, 0x2000
	s_add_u32 s78, s50, 0x100000
	v_lshl_add_u64 v[228:229], s[50:51], 0, v[136:137]
	s_addc_u32 s79, s51, 0
	s_add_i32 s77, s70, s56
	global_load_lds_dwordx4 v[228:229], off
	v_lshl_add_u64 v[230:231], s[78:79], 0, v[132:133]
	s_mov_b32 m0, s77
	v_lshl_add_u64 v[232:233], s[52:53], 0, v[134:135]
	global_load_lds_dwordx4 v[230:231], off
	v_lshl_add_u64 v[230:231], s[78:79], 0, v[136:137]
	s_add_i32 m0, s77, 0x2000
	s_nop 0
	global_load_lds_dwordx4 v[230:231], off
	v_lshl_add_u64 v[230:231], s[52:53], 0, v[130:131]
	s_mov_b32 m0, s9
	s_nop 0
	global_load_lds_dwordx4 v[230:231], off
	s_mov_b32 m0, s57
	s_nop 0
	global_load_lds_dwordx4 v[232:233], off
	s_waitcnt vmcnt(8)
	s_waitcnt lgkmcnt(0)
	s_setprio 1
	s_barrier
; #define PG8_STAGE(bufoff, gbase, voff) do { _Pragma("unroll") for (int _i = 0; _i < 2; ++_i) \
;         __builtin_amdgcn_global_load_lds((const unsigned*)((const char*)(gbase) + (voff)[_i]), (PG8_LAS unsigned*)(lds + (bufoff) + ldsw + _i * 8192), 16, 0, 0); } while (0)
; #define PG8_LDA(dst, b, h) do { _Pragma("unroll") for (int m = 0; m < 4; ++m) _Pragma("unroll") for (int k = 0; k < 2; ++k) dst[m][k] = *(const PG8_LAS bf16x8*)(lds + PG8_SA(b, h) + aoff + m * 2048 + k * 1024); } while (0)
; #define PG8_LDB(dst, b, h) do { _Pragma("unroll") for (int n = 0; n < 2; ++n) _Pragma("unroll") for (int k = 0; k < 2; ++k) dst[n][k] = *(const PG8_LAS bf16x8*)(lds + PG8_SB(b, h) + boff + n * 2048 + k * 1024); } while (0)
; #define PG8_MMA(ai, bj, At, Bt) do { __builtin_amdgcn_s_setprio(1); _Pragma("unroll") for (int m = 0; m < 4; ++m) _Pragma("unroll") for (int n = 0; n < 2; ++n) _Pragma("unroll") for (int k = 0; k < 2; ++k) \
;         acc[ai][bj][m][n] = __builtin_amdgcn_mfma_f32_16x16x32_bf16(Bt[n][k], At[m][k], acc[ai][bj][m][n], 0, 0, 0); __builtin_amdgcn_s_setprio(0); } while (0)
; #define PG8_WAIT_V(n) asm volatile("s_waitcnt vmcnt(" #n ")" ::: "memory")
; #define PG8_WAIT_L(n) asm volatile("s_waitcnt lgkmcnt(" #n ")" ::: "memory")
; #define PG8_BAR __builtin_amdgcn_s_barrier()
; #define PG8_SCHED __builtin_amdgcn_sched_barrier(0)
; template <class Epi, class Sched, bool ALIGN_EPI = false, bool SP2 = false>
; __device__ __forceinline__ void gemm_phase(PG8_LAS unsigned char* lds, const Gemm g, const Sched& S, const Epi& E) {
;     ...
;             PG8_WAIT_V(8); PG8_WAIT_L(0); PG8_BAR; PG8_MMA(1, 0, At, B0); PG8_MMA(1, 1, At, B1); PG8_BAR; PG8_SCHED;
;             PG8_LDB(B0, 1, 0); PG8_LDB(B1, 1, 1); PG8_SCHED; PG8_LDA(At, 1, 0); PG8_STAGE(PG8_SA(0, 1), a2 + hstep, voffA);
;             PG8_WAIT_V(8); PG8_WAIT_L(0); PG8_BAR; PG8_MMA(0, 0, At, B0); PG8_MMA(0, 1, At, B1); PG8_BAR; PG8_SCHED;
;             PG8_LDA(At, 1, 1); PG8_STAGE(PG8_SB(1, 0), b3, voffB); PG8_STAGE(PG8_SB(1, 1), b3 + hstep, voffB); PG8_STAGE(PG8_SA(1, 0), a3, voffA);
	v_mfma_f32_16x16x32_bf16 v[62:65], v[146:149], v[192:195], 0
	v_mfma_f32_16x16x32_bf16 v[58:61], v[168:171], v[192:195], 0
	v_mfma_f32_16x16x32_bf16 v[46:49], v[146:149], v[202:205], 0
	v_mfma_f32_16x16x32_bf16 v[42:45], v[168:171], v[202:205], 0
	v_mfma_f32_16x16x32_bf16 v[30:33], v[146:149], v[210:213], 0
	v_mfma_f32_16x16x32_bf16 v[26:29], v[168:171], v[210:213], 0
	v_mfma_f32_16x16x32_bf16 v[14:17], v[146:149], v[218:221], 0
	v_mfma_f32_16x16x32_bf16 v[10:13], v[168:171], v[218:221], 0
	v_mfma_f32_16x16x32_bf16 v[62:65], v[164:167], v[198:201], v[62:65]
	v_mfma_f32_16x16x32_bf16 v[58:61], v[172:175], v[198:201], v[58:61]
	v_mfma_f32_16x16x32_bf16 v[46:49], v[164:167], v[206:209], v[46:49]
	v_mfma_f32_16x16x32_bf16 v[42:45], v[172:175], v[206:209], v[42:45]
	v_mfma_f32_16x16x32_bf16 v[30:33], v[164:167], v[214:217], v[30:33]
	v_mfma_f32_16x16x32_bf16 v[26:29], v[172:175], v[214:217], v[26:29]
	v_mfma_f32_16x16x32_bf16 v[14:17], v[164:167], v[222:225], v[14:17]
	v_mfma_f32_16x16x32_bf16 v[10:13], v[172:175], v[222:225], v[10:13]
	s_setprio 0
	s_setprio 1
	v_mfma_f32_16x16x32_bf16 v[54:57], v[176:179], v[192:195], 0
	v_mfma_f32_16x16x32_bf16 v[50:53], v[184:187], v[192:195], 0
	v_mfma_f32_16x16x32_bf16 v[38:41], v[176:179], v[202:205], 0
	v_mfma_f32_16x16x32_bf16 v[34:37], v[184:187], v[202:205], 0
	v_mfma_f32_16x16x32_bf16 v[22:25], v[176:179], v[210:213], 0
	v_mfma_f32_16x16x32_bf16 v[18:21], v[184:187], v[210:213], 0
	v_mfma_f32_16x16x32_bf16 v[6:9], v[176:179], v[218:221], 0
	v_mfma_f32_16x16x32_bf16 v[2:5], v[184:187], v[218:221], 0
	v_mfma_f32_16x16x32_bf16 v[54:57], v[180:183], v[198:201], v[54:57]
	v_mfma_f32_16x16x32_bf16 v[50:53], v[188:191], v[198:201], v[50:53]
	v_mfma_f32_16x16x32_bf16 v[38:41], v[180:183], v[206:209], v[38:41]
	v_mfma_f32_16x16x32_bf16 v[34:37], v[188:191], v[206:209], v[34:37]
	v_mfma_f32_16x16x32_bf16 v[22:25], v[180:183], v[214:217], v[22:25]
	v_mfma_f32_16x16x32_bf16 v[18:21], v[188:191], v[214:217], v[18:21]
	v_mfma_f32_16x16x32_bf16 v[6:9], v[180:183], v[222:225], v[6:9]
	v_mfma_f32_16x16x32_bf16 v[2:5], v[188:191], v[222:225], v[2:5]
	s_setprio 0
	s_barrier
	s_add_i32 s77, 0, 0x18000
	s_add_i32 s78, 0, 0x1c000
	v_add_u32_e32 v172, s77, v151
	v_add_u32_e32 v188, s78, v151
	ds_read_b128 v[146:149], v172
	ds_read_b128 v[164:167], v172 offset:1024
	ds_read_b128 v[168:171], v172 offset:2048
	ds_read_b128 v[172:175], v172 offset:3072
	ds_read_b128 v[176:179], v188
	ds_read_b128 v[180:183], v188 offset:1024
	ds_read_b128 v[184:187], v188 offset:2048
	ds_read_b128 v[188:191], v188 offset:3072
	s_add_u32 s52, s52, 0x100000
	s_addc_u32 s53, s53, 0
	s_mov_b32 m0, s58
	v_lshl_add_u64 v[234:235], s[52:53], 0, v[130:131]
	ds_read_b128 v[192:195], v162 offset:32768
	ds_read_b128 v[198:201], v162 offset:33792
	ds_read_b128 v[202:205], v162 offset:34816
	ds_read_b128 v[206:209], v162 offset:35840
	ds_read_b128 v[210:213], v162 offset:36864
	ds_read_b128 v[214:217], v162 offset:37888
	ds_read_b128 v[218:221], v162 offset:38912
	ds_read_b128 v[222:225], v162 offset:39936
	global_load_lds_dwordx4 v[234:235], off
	v_lshl_add_u64 v[234:235], s[52:53], 0, v[134:135]
	s_mov_b32 m0, s59
	s_nop 0
	global_load_lds_dwordx4 v[234:235], off
	s_waitcnt vmcnt(8)
	s_waitcnt lgkmcnt(0)
	s_setprio 1
	s_barrier
	v_mfma_f32_16x16x32_bf16 v[126:129], v[146:149], v[192:195], v[126:129]
	v_mfma_f32_16x16x32_bf16 v[122:125], v[168:171], v[192:195], v[122:125]
	v_mfma_f32_16x16x32_bf16 v[110:113], v[146:149], v[202:205], v[110:113]
	v_mfma_f32_16x16x32_bf16 v[106:109], v[168:171], v[202:205], v[106:109]
	v_mfma_f32_16x16x32_bf16 v[94:97], v[146:149], v[210:213], v[94:97]
	v_mfma_f32_16x16x32_bf16 v[90:93], v[168:171], v[210:213], v[90:93]
	v_mfma_f32_16x16x32_bf16 v[78:81], v[146:149], v[218:221], v[78:81]
	v_mfma_f32_16x16x32_bf16 v[74:77], v[168:171], v[218:221], v[74:77]
	v_mfma_f32_16x16x32_bf16 v[126:129], v[164:167], v[198:201], v[126:129]
	v_mfma_f32_16x16x32_bf16 v[122:125], v[172:175], v[198:201], v[122:125]
	v_mfma_f32_16x16x32_bf16 v[110:113], v[164:167], v[206:209], v[110:113]
	v_mfma_f32_16x16x32_bf16 v[106:109], v[172:175], v[206:209], v[106:109]
	v_mfma_f32_16x16x32_bf16 v[94:97], v[164:167], v[214:217], v[94:97]
	v_mfma_f32_16x16x32_bf16 v[90:93], v[172:175], v[214:217], v[90:93]
	v_mfma_f32_16x16x32_bf16 v[78:81], v[164:167], v[222:225], v[78:81]
	v_mfma_f32_16x16x32_bf16 v[74:77], v[172:175], v[222:225], v[74:77]
	s_setprio 0
	s_setprio 1
	v_mfma_f32_16x16x32_bf16 v[118:121], v[176:179], v[192:195], v[118:121]
	v_mfma_f32_16x16x32_bf16 v[114:117], v[184:187], v[192:195], v[114:117]
	v_mfma_f32_16x16x32_bf16 v[102:105], v[176:179], v[202:205], v[102:105]
	v_mfma_f32_16x16x32_bf16 v[98:101], v[184:187], v[202:205], v[98:101]
	v_mfma_f32_16x16x32_bf16 v[86:89], v[176:179], v[210:213], v[86:89]
	v_mfma_f32_16x16x32_bf16 v[82:85], v[184:187], v[210:213], v[82:85]
	v_mfma_f32_16x16x32_bf16 v[70:73], v[176:179], v[218:221], v[70:73]
	v_mfma_f32_16x16x32_bf16 v[66:69], v[184:187], v[218:221], v[66:69]
	v_mfma_f32_16x16x32_bf16 v[118:121], v[180:183], v[198:201], v[118:121]
	v_mfma_f32_16x16x32_bf16 v[114:117], v[188:191], v[198:201], v[114:117]
	v_mfma_f32_16x16x32_bf16 v[102:105], v[180:183], v[206:209], v[102:105]
	v_mfma_f32_16x16x32_bf16 v[98:101], v[188:191], v[206:209], v[98:101]
	v_mfma_f32_16x16x32_bf16 v[86:89], v[180:183], v[214:217], v[86:89]
	v_mfma_f32_16x16x32_bf16 v[82:85], v[188:191], v[214:217], v[82:85]
	v_mfma_f32_16x16x32_bf16 v[70:73], v[180:183], v[222:225], v[70:73]
	v_mfma_f32_16x16x32_bf16 v[66:69], v[188:191], v[222:225], v[66:69]
	s_setprio 0
	s_barrier
; #define PG8_STAGE(bufoff, gbase, voff) do { _Pragma("unroll") for (int _i = 0; _i < 2; ++_i) \
;         __builtin_amdgcn_global_load_lds((const unsigned*)((const char*)(gbase) + (voff)[_i]), (PG8_LAS unsigned*)(lds + (bufoff) + ldsw + _i * 8192), 16, 0, 0); } while (0)
; #define PG8_LDA(dst, b, h) do { _Pragma("unroll") for (int m = 0; m < 4; ++m) _Pragma("unroll") for (int k = 0; k < 2; ++k) dst[m][k] = *(const PG8_LAS bf16x8*)(lds + PG8_SA(b, h) + aoff + m * 2048 + k * 1024); } while (0)
; #define PG8_MMA(ai, bj, At, Bt) do { __builtin_amdgcn_s_setprio(1); _Pragma("unroll") for (int m = 0; m < 4; ++m) _Pragma("unroll") for (int n = 0; n < 2; ++n) _Pragma("unroll") for (int k = 0; k < 2; ++k) \
;         acc[ai][bj][m][n] = __builtin_amdgcn_mfma_f32_16x16x32_bf16(Bt[n][k], At[m][k], acc[ai][bj][m][n], 0, 0, 0); __builtin_amdgcn_s_setprio(0); } while (0)
; #define PG8_WAIT_V(n) asm volatile("s_waitcnt vmcnt(" #n ")" ::: "memory")
; #define PG8_WAIT_L(n) asm volatile("s_waitcnt lgkmcnt(" #n ")" ::: "memory")
; #define PG8_BAR __builtin_amdgcn_s_barrier()
; #define PG8_SCHED __builtin_amdgcn_sched_barrier(0)
; template <class Epi, class Sched, bool ALIGN_EPI = false, bool SP2 = false>
; __device__ __forceinline__ void gemm_phase(PG8_LAS unsigned char* lds, const Gemm g, const Sched& S, const Epi& E) {
;     ...
;         for (int t = 0; t < nt; t += 2) {
;     ...
;             PG8_LDA(At, 1, 1); PG8_STAGE(PG8_SB(1, 0), b3, voffB); PG8_STAGE(PG8_SB(1, 1), b3 + hstep, voffB); PG8_STAGE(PG8_SA(1, 0), a3, voffA);
;             PG8_WAIT_V(8); PG8_WAIT_L(0); PG8_BAR; PG8_MMA(1, 0, At, B0); PG8_MMA(1, 1, At, B1); PG8_BAR; PG8_SCHED;
	s_add_i32 s52, s77, s56
	v_lshl_add_u64 v[226:227], v[226:227], 0, s[36:37]
	s_mov_b32 m0, s52
	ds_read_b128 v[192:195], v162 offset:49152
	ds_read_b128 v[198:201], v162 offset:50176
	ds_read_b128 v[202:205], v162 offset:51200
	ds_read_b128 v[206:209], v162 offset:52224
	ds_read_b128 v[210:213], v162 offset:53248
	ds_read_b128 v[214:217], v162 offset:54272
	ds_read_b128 v[218:221], v162 offset:55296
	ds_read_b128 v[222:225], v162 offset:56320
	global_load_lds_dwordx4 v[226:227], off
	s_add_i32 m0, s52, 0x2000
	s_add_u32 s50, s50, 0x100080
	v_lshl_add_u64 v[226:227], v[228:229], 0, s[36:37]
	s_addc_u32 s51, s51, 0
	s_add_i32 s52, s78, s56
	global_load_lds_dwordx4 v[226:227], off
	v_lshl_add_u64 v[226:227], s[50:51], 0, v[132:133]
	s_mov_b32 m0, s52
	s_nop 0
	global_load_lds_dwordx4 v[226:227], off
	v_lshl_add_u64 v[226:227], s[50:51], 0, v[136:137]
	s_add_i32 m0, s52, 0x2000
	s_nop 0
	global_load_lds_dwordx4 v[226:227], off
	v_lshl_add_u64 v[226:227], v[230:231], 0, s[36:37]
	s_mov_b32 m0, s61
	s_nop 0
	global_load_lds_dwordx4 v[226:227], off
	v_lshl_add_u64 v[226:227], v[232:233], 0, s[36:37]
	s_mov_b32 m0, s62
	s_nop 0
	global_load_lds_dwordx4 v[226:227], off
	s_waitcnt vmcnt(8)
	s_waitcnt lgkmcnt(0)
	s_setprio 1
	s_barrier
	v_mfma_f32_16x16x32_bf16 v[62:65], v[146:149], v[192:195], v[62:65]
	v_mfma_f32_16x16x32_bf16 v[58:61], v[168:171], v[192:195], v[58:61]
	v_mfma_f32_16x16x32_bf16 v[46:49], v[146:149], v[202:205], v[46:49]
	v_mfma_f32_16x16x32_bf16 v[42:45], v[168:171], v[202:205], v[42:45]
	v_mfma_f32_16x16x32_bf16 v[30:33], v[146:149], v[210:213], v[30:33]
	v_mfma_f32_16x16x32_bf16 v[26:29], v[168:171], v[210:213], v[26:29]
	v_mfma_f32_16x16x32_bf16 v[14:17], v[146:149], v[218:221], v[14:17]
	v_mfma_f32_16x16x32_bf16 v[10:13], v[168:171], v[218:221], v[10:13]
	v_mfma_f32_16x16x32_bf16 v[62:65], v[164:167], v[198:201], v[62:65]
	v_mfma_f32_16x16x32_bf16 v[58:61], v[172:175], v[198:201], v[58:61]
	v_mfma_f32_16x16x32_bf16 v[46:49], v[164:167], v[206:209], v[46:49]
	v_mfma_f32_16x16x32_bf16 v[42:45], v[172:175], v[206:209], v[42:45]
	v_mfma_f32_16x16x32_bf16 v[30:33], v[164:167], v[214:217], v[30:33]
	v_mfma_f32_16x16x32_bf16 v[26:29], v[172:175], v[214:217], v[26:29]
	v_mfma_f32_16x16x32_bf16 v[14:17], v[164:167], v[222:225], v[14:17]
	v_mfma_f32_16x16x32_bf16 v[10:13], v[172:175], v[222:225], v[10:13]
	s_setprio 0
	s_setprio 1
	v_mfma_f32_16x16x32_bf16 v[54:57], v[176:179], v[192:195], v[54:57]
	v_mfma_f32_16x16x32_bf16 v[50:53], v[184:187], v[192:195], v[50:53]
	v_mfma_f32_16x16x32_bf16 v[38:41], v[176:179], v[202:205], v[38:41]
	v_mfma_f32_16x16x32_bf16 v[34:37], v[184:187], v[202:205], v[34:37]
	v_mfma_f32_16x16x32_bf16 v[22:25], v[176:179], v[210:213], v[22:25]
	v_mfma_f32_16x16x32_bf16 v[18:21], v[184:187], v[210:213], v[18:21]
	v_mfma_f32_16x16x32_bf16 v[6:9], v[176:179], v[218:221], v[6:9]
	v_mfma_f32_16x16x32_bf16 v[2:5], v[184:187], v[218:221], v[2:5]
	v_mfma_f32_16x16x32_bf16 v[54:57], v[180:183], v[198:201], v[54:57]
	v_mfma_f32_16x16x32_bf16 v[50:53], v[188:191], v[198:201], v[50:53]
	v_mfma_f32_16x16x32_bf16 v[38:41], v[180:183], v[206:209], v[38:41]
	v_mfma_f32_16x16x32_bf16 v[34:37], v[188:191], v[206:209], v[34:37]
	v_mfma_f32_16x16x32_bf16 v[22:25], v[180:183], v[214:217], v[22:25]
	v_mfma_f32_16x16x32_bf16 v[18:21], v[188:191], v[214:217], v[18:21]
	v_mfma_f32_16x16x32_bf16 v[6:9], v[180:183], v[222:225], v[6:9]
	v_mfma_f32_16x16x32_bf16 v[2:5], v[188:191], v[222:225], v[2:5]
	s_setprio 0
	s_barrier
	s_add_i32 s76, s76, 2
	s_add_u32 s48, s48, 0x100
	s_addc_u32 s49, s49, 0
	s_add_u32 s74, s74, 0x100
	s_addc_u32 s75, s75, 0
	s_cmp_gt_u32 s76, 61

; #define PG8_STAGE(bufoff, gbase, voff) do { _Pragma("unroll") for (int _i = 0; _i < 2; ++_i) \
;         __builtin_amdgcn_global_load_lds((const unsigned*)((const char*)(gbase) + (voff)[_i]), (PG8_LAS unsigned*)(lds + (bufoff) + ldsw + _i * 8192), 16, 0, 0); } while (0)
; #define PG8_LDA(dst, b, h) do { _Pragma("unroll") for (int m = 0; m < 4; ++m) _Pragma("unroll") for (int k = 0; k < 2; ++k) dst[m][k] = *(const PG8_LAS bf16x8*)(lds + PG8_SA(b, h) + aoff + m * 2048 + k * 1024); } while (0)
; #define PG8_WAIT_V(n) asm volatile("s_waitcnt vmcnt(" #n ")" ::: "memory")
; #define PG8_WAIT_L(n) asm volatile("s_waitcnt lgkmcnt(" #n ")" ::: "memory")
; template <class Epi, class Sched, bool ALIGN_EPI = false, bool SP2 = false>
; __device__ __forceinline__ void gemm_phase(PG8_LAS unsigned char* lds, const Gemm g, const Sched& S, const Epi& E) {
;     ...
;         const bool has_next = S.next(ui + 1, nxt);
;         const char* nA = has_next ? (const char*)g.A + (size_t)nxt.pm * tstep : cA; const char* nB = has_next ? (const char*)g.Bt + (size_t)nxt.pn * tstep : cB;
;         for (int t = 0; t < nt; t += 2) {
;             const bool last = (t == nt - 2);
;             const char* a1 = cA + (size_t)(t + 1) * kstep;
;             const char* a2 = last ? nA : cA + (size_t)(t + 2) * kstep; const char* b2 = last ? nB : cB + (size_t)(t + 2) * kstep;
;             const char* a3 = a2 + kstep; const char* b3 = b2 + kstep;
;             if (last && has_next) S.a_ready(nxt);
;             if constexpr (SP2) {
;             PG8_LDB(B0, 0, 0); PG8_LDB(B1, 0, 1); PG8_SCHED; PG8_LDA(At, 0, 0); PG8_STAGE(PG8_SA(1, 1), a1 + hstep, voffA);
;             PG8_WAIT_V(8); PG8_WAIT_L(0); PG8_BAR; PG8_MMA(0, 0, At, B0); PG8_MMA(0, 1, At, B1); PG8_BAR; PG8_SCHED;
;             PG8_LDA(At, 0, 1); PG8_STAGE(PG8_SB(0, 0), b2, voffB); PG8_STAGE(PG8_SB(0, 1), b2 + hstep, voffB); PG8_STAGE(PG8_SA(0, 0), a2, voffA);
;             PG8_WAIT_V(8); PG8_WAIT_L(0); PG8_BAR; PG8_MMA(1, 0, At, B0); PG8_MMA(1, 1, At, B1); PG8_BAR; PG8_SCHED;
;     ...
; #pragma unroll
;         for (int a = 0; a < 2; ++a)
; #pragma unroll
;             for (int b = 0; b < 2; ++b)
; #pragma unroll
;                 for (int m = 0; m < 4; ++m)
; #pragma unroll
;                     for (int n = 0; n < 2; ++n) acc[a][b][m][n] = (f32x4){0.f, 0.f, 0.f, 0.f};
;         cur = nxt; cA = nA; cB = nB; ++ui;
.LBB0_880:
	s_ashr_i32 s37, s36, 31
	s_lshl_b64 s[38:39], s[36:37], 21
	s_add_u32 s38, s19, s38
	s_addc_u32 s39, s21, s39
	s_and_b64 s[40:41], s[2:3], exec
	s_cselect_b32 s37, s39, s45
	s_cselect_b32 s70, s38, s44
	s_ashr_i32 s35, s34, 31
	s_lshl_b64 s[40:41], s[34:35], 21
	s_add_u32 s40, s50, s40
	s_addc_u32 s41, s51, s41
	s_and_b64 s[48:49], s[2:3], exec
	s_cselect_b32 s35, s41, s47
	s_cselect_b32 s71, s40, s46
	s_add_u32 s44, s44, 0x100080
	s_addc_u32 s45, s45, 0
	s_add_u32 s72, s46, 0x100
	s_addc_u32 s73, s47, 0
	s_mov_b32 s74, -2
	ds_read_b128 v[156:159], v152
	ds_read_b128 v[160:163], v152 offset:1024
	ds_read_b128 v[164:167], v152 offset:2048
	ds_read_b128 v[168:171], v152 offset:3072
	ds_read_b128 v[172:175], v153
	ds_read_b128 v[176:179], v153 offset:1024
	ds_read_b128 v[180:183], v153 offset:2048
	ds_read_b128 v[184:187], v153 offset:3072
	s_add_u32 s46, s44, 0xfff00080
	s_addc_u32 s47, s45, -1
	s_cmp_eq_u32 s74, 60
	s_cselect_b32 s49, s37, s47
	s_cselect_b32 s48, s70, s46
	s_cselect_b32 s47, s35, s73
	s_cselect_b32 s46, s71, s72
	v_lshl_add_u64 v[146:147], s[44:45], 0, v[138:139]
	s_add_i32 m0, s43, 0xc000
	ds_read_b128 v[188:191], v154
	ds_read_b128 v[192:195], v154 offset:1024
	ds_read_b128 v[198:201], v154 offset:2048
	ds_read_b128 v[202:205], v154 offset:3072
	ds_read_b128 v[206:209], v154 offset:4096
	ds_read_b128 v[210:213], v154 offset:5120
	ds_read_b128 v[214:217], v154 offset:6144
	ds_read_b128 v[218:221], v154 offset:7168
	global_load_lds_dwordx4 v[146:147], off
	v_lshl_add_u64 v[146:147], s[44:45], 0, v[140:141]
	s_add_i32 m0, s43, 0xe000
	s_nop 0
	global_load_lds_dwordx4 v[146:147], off
	s_waitcnt vmcnt(8)
	s_waitcnt lgkmcnt(0)
	s_setprio 1
	s_barrier
	v_mfma_f32_16x16x32_bf16 v[122:125], v[156:159], v[188:191], 0
	v_mfma_f32_16x16x32_bf16 v[114:117], v[164:167], v[188:191], 0
	v_mfma_f32_16x16x32_bf16 v[106:109], v[156:159], v[198:201], 0
	v_mfma_f32_16x16x32_bf16 v[98:101], v[164:167], v[198:201], 0
	v_mfma_f32_16x16x32_bf16 v[90:93], v[156:159], v[206:209], 0
	v_mfma_f32_16x16x32_bf16 v[82:85], v[164:167], v[206:209], 0
	v_mfma_f32_16x16x32_bf16 v[74:77], v[156:159], v[214:217], 0
	v_mfma_f32_16x16x32_bf16 v[66:69], v[164:167], v[214:217], 0
	v_mfma_f32_16x16x32_bf16 v[122:125], v[160:163], v[192:195], v[122:125]
	v_mfma_f32_16x16x32_bf16 v[114:117], v[168:171], v[192:195], v[114:117]
	v_mfma_f32_16x16x32_bf16 v[106:109], v[160:163], v[202:205], v[106:109]
	v_mfma_f32_16x16x32_bf16 v[98:101], v[168:171], v[202:205], v[98:101]
	v_mfma_f32_16x16x32_bf16 v[90:93], v[160:163], v[210:213], v[90:93]
	v_mfma_f32_16x16x32_bf16 v[82:85], v[168:171], v[210:213], v[82:85]
	v_mfma_f32_16x16x32_bf16 v[74:77], v[160:163], v[218:221], v[74:77]
	v_mfma_f32_16x16x32_bf16 v[66:69], v[168:171], v[218:221], v[66:69]
	s_setprio 0
	s_setprio 1
	v_mfma_f32_16x16x32_bf16 v[126:129], v[172:175], v[188:191], 0
	v_mfma_f32_16x16x32_bf16 v[118:121], v[180:183], v[188:191], 0
	v_mfma_f32_16x16x32_bf16 v[110:113], v[172:175], v[198:201], 0
	v_mfma_f32_16x16x32_bf16 v[102:105], v[180:183], v[198:201], 0
	v_mfma_f32_16x16x32_bf16 v[94:97], v[172:175], v[206:209], 0
	v_mfma_f32_16x16x32_bf16 v[86:89], v[180:183], v[206:209], 0
	v_mfma_f32_16x16x32_bf16 v[78:81], v[172:175], v[214:217], 0
	v_mfma_f32_16x16x32_bf16 v[70:73], v[180:183], v[214:217], 0
	v_mfma_f32_16x16x32_bf16 v[126:129], v[176:179], v[192:195], v[126:129]
	v_mfma_f32_16x16x32_bf16 v[118:121], v[184:187], v[192:195], v[118:121]
	v_mfma_f32_16x16x32_bf16 v[110:113], v[176:179], v[202:205], v[110:113]
	v_mfma_f32_16x16x32_bf16 v[102:105], v[184:187], v[202:205], v[102:105]
	v_mfma_f32_16x16x32_bf16 v[94:97], v[176:179], v[210:213], v[94:97]
	v_mfma_f32_16x16x32_bf16 v[86:89], v[184:187], v[210:213], v[86:89]
	v_mfma_f32_16x16x32_bf16 v[78:81], v[176:179], v[218:221], v[78:81]
	v_mfma_f32_16x16x32_bf16 v[70:73], v[184:187], v[218:221], v[70:73]
	s_setprio 0
	s_barrier
	s_add_i32 s75, s63, s52
	v_lshl_add_u64 v[146:147], s[46:47], 0, v[134:135]
	s_mov_b32 m0, s75
	ds_read_b128 v[188:191], v154 offset:16384
	ds_read_b128 v[192:195], v154 offset:17408
	ds_read_b128 v[198:201], v154 offset:18432
	ds_read_b128 v[202:205], v154 offset:19456
	ds_read_b128 v[206:209], v154 offset:20480
	ds_read_b128 v[210:213], v154 offset:21504
	ds_read_b128 v[214:217], v154 offset:22528
	ds_read_b128 v[218:221], v154 offset:23552
	global_load_lds_dwordx4 v[146:147], off
	s_add_i32 m0, s75, 0x2000
	s_add_u32 s76, s46, 0x100000
	v_lshl_add_u64 v[222:223], s[46:47], 0, v[130:131]
	s_addc_u32 s77, s47, 0
	s_add_i32 s75, s67, s52
	global_load_lds_dwordx4 v[222:223], off
	v_lshl_add_u64 v[224:225], s[76:77], 0, v[134:135]
	s_mov_b32 m0, s75
	v_lshl_add_u64 v[226:227], s[48:49], 0, v[132:133]
	global_load_lds_dwordx4 v[224:225], off
	v_lshl_add_u64 v[224:225], s[76:77], 0, v[130:131]
	s_add_i32 m0, s75, 0x2000
	s_nop 0
	global_load_lds_dwordx4 v[224:225], off
	v_lshl_add_u64 v[224:225], s[48:49], 0, v[136:137]
	s_mov_b32 m0, s43
	s_nop 0
	global_load_lds_dwordx4 v[224:225], off
	s_mov_b32 m0, s55
	s_nop 0
	global_load_lds_dwordx4 v[226:227], off
	s_waitcnt vmcnt(8)
	s_waitcnt lgkmcnt(0)
	s_setprio 1
	s_barrier
; #define PG8_STAGE(bufoff, gbase, voff) do { _Pragma("unroll") for (int _i = 0; _i < 2; ++_i) \
;         __builtin_amdgcn_global_load_lds((const unsigned*)((const char*)(gbase) + (voff)[_i]), (PG8_LAS unsigned*)(lds + (bufoff) + ldsw + _i * 8192), 16, 0, 0); } while (0)
; #define PG8_LDA(dst, b, h) do { _Pragma("unroll") for (int m = 0; m < 4; ++m) _Pragma("unroll") for (int k = 0; k < 2; ++k) dst[m][k] = *(const PG8_LAS bf16x8*)(lds + PG8_SA(b, h) + aoff + m * 2048 + k * 1024); } while (0)
; #define PG8_LDB(dst, b, h) do { _Pragma("unroll") for (int n = 0; n < 2; ++n) _Pragma("unroll") for (int k = 0; k < 2; ++k) dst[n][k] = *(const PG8_LAS bf16x8*)(lds + PG8_SB(b, h) + boff + n * 2048 + k * 1024); } while (0)
; #define PG8_MMA(ai, bj, At, Bt) do { __builtin_amdgcn_s_setprio(1); _Pragma("unroll") for (int m = 0; m < 4; ++m) _Pragma("unroll") for (int n = 0; n < 2; ++n) _Pragma("unroll") for (int k = 0; k < 2; ++k) \
;         acc[ai][bj][m][n] = __builtin_amdgcn_mfma_f32_16x16x32_bf16(Bt[n][k], At[m][k], acc[ai][bj][m][n], 0, 0, 0); __builtin_amdgcn_s_setprio(0); } while (0)
; #define PG8_WAIT_V(n) asm volatile("s_waitcnt vmcnt(" #n ")" ::: "memory")
; #define PG8_WAIT_L(n) asm volatile("s_waitcnt lgkmcnt(" #n ")" ::: "memory")
; #define PG8_BAR __builtin_amdgcn_s_barrier()
; #define PG8_SCHED __builtin_amdgcn_sched_barrier(0)
; template <class Epi, class Sched, bool ALIGN_EPI = false, bool SP2 = false>
; __device__ __forceinline__ void gemm_phase(PG8_LAS unsigned char* lds, const Gemm g, const Sched& S, const Epi& E) {
;     ...
;             PG8_WAIT_V(8); PG8_WAIT_L(0); PG8_BAR; PG8_MMA(1, 0, At, B0); PG8_MMA(1, 1, At, B1); PG8_BAR; PG8_SCHED;
;             PG8_LDB(B0, 1, 0); PG8_LDB(B1, 1, 1); PG8_SCHED; PG8_LDA(At, 1, 0); PG8_STAGE(PG8_SA(0, 1), a2 + hstep, voffA);
;             PG8_WAIT_V(8); PG8_WAIT_L(0); PG8_BAR; PG8_MMA(0, 0, At, B0); PG8_MMA(0, 1, At, B1); PG8_BAR; PG8_SCHED;
;             PG8_LDA(At, 1, 1); PG8_STAGE(PG8_SB(1, 0), b3, voffB); PG8_STAGE(PG8_SB(1, 1), b3 + hstep, voffB); PG8_STAGE(PG8_SA(1, 0), a3, voffA);
	v_mfma_f32_16x16x32_bf16 v[58:61], v[156:159], v[188:191], 0
	v_mfma_f32_16x16x32_bf16 v[50:53], v[164:167], v[188:191], 0
	v_mfma_f32_16x16x32_bf16 v[42:45], v[156:159], v[198:201], 0
	v_mfma_f32_16x16x32_bf16 v[34:37], v[164:167], v[198:201], 0
	v_mfma_f32_16x16x32_bf16 v[26:29], v[156:159], v[206:209], 0
	v_mfma_f32_16x16x32_bf16 v[18:21], v[164:167], v[206:209], 0
	v_mfma_f32_16x16x32_bf16 v[10:13], v[156:159], v[214:217], 0
	v_mfma_f32_16x16x32_bf16 v[6:9], v[164:167], v[214:217], 0
	v_mfma_f32_16x16x32_bf16 v[58:61], v[160:163], v[192:195], v[58:61]
	v_mfma_f32_16x16x32_bf16 v[50:53], v[168:171], v[192:195], v[50:53]
	v_mfma_f32_16x16x32_bf16 v[42:45], v[160:163], v[202:205], v[42:45]
	v_mfma_f32_16x16x32_bf16 v[34:37], v[168:171], v[202:205], v[34:37]
	v_mfma_f32_16x16x32_bf16 v[26:29], v[160:163], v[210:213], v[26:29]
	v_mfma_f32_16x16x32_bf16 v[18:21], v[168:171], v[210:213], v[18:21]
	v_mfma_f32_16x16x32_bf16 v[10:13], v[160:163], v[218:221], v[10:13]
	v_mfma_f32_16x16x32_bf16 v[6:9], v[168:171], v[218:221], v[6:9]
	s_setprio 0
	s_setprio 1
	v_mfma_f32_16x16x32_bf16 v[62:65], v[172:175], v[188:191], 0
	v_mfma_f32_16x16x32_bf16 v[54:57], v[180:183], v[188:191], 0
	v_mfma_f32_16x16x32_bf16 v[46:49], v[172:175], v[198:201], 0
	v_mfma_f32_16x16x32_bf16 v[38:41], v[180:183], v[198:201], 0
	v_mfma_f32_16x16x32_bf16 v[30:33], v[172:175], v[206:209], 0
	v_mfma_f32_16x16x32_bf16 v[22:25], v[180:183], v[206:209], 0
	v_mfma_f32_16x16x32_bf16 v[14:17], v[172:175], v[214:217], 0
	v_mfma_f32_16x16x32_bf16 v[2:5], v[180:183], v[214:217], 0
	v_mfma_f32_16x16x32_bf16 v[62:65], v[176:179], v[192:195], v[62:65]
	v_mfma_f32_16x16x32_bf16 v[54:57], v[184:187], v[192:195], v[54:57]
	v_mfma_f32_16x16x32_bf16 v[46:49], v[176:179], v[202:205], v[46:49]
	v_mfma_f32_16x16x32_bf16 v[38:41], v[184:187], v[202:205], v[38:41]
	v_mfma_f32_16x16x32_bf16 v[30:33], v[176:179], v[210:213], v[30:33]
	v_mfma_f32_16x16x32_bf16 v[22:25], v[184:187], v[210:213], v[22:25]
	v_mfma_f32_16x16x32_bf16 v[14:17], v[176:179], v[218:221], v[14:17]
	v_mfma_f32_16x16x32_bf16 v[2:5], v[184:187], v[218:221], v[2:5]
	s_setprio 0
	s_barrier
	s_add_i32 s75, 0, 0x18000
	v_add_u32_e32 v155, s75, v150
	s_add_i32 s76, 0, 0x1c000
	ds_read_b128 v[156:159], v155
	ds_read_b128 v[160:163], v155 offset:1024
	ds_read_b128 v[164:167], v155 offset:2048
	ds_read_b128 v[168:171], v155 offset:3072
	v_add_u32_e32 v155, s76, v150
	ds_read_b128 v[172:175], v155
	ds_read_b128 v[176:179], v155 offset:1024
	ds_read_b128 v[180:183], v155 offset:2048
	ds_read_b128 v[184:187], v155 offset:3072
	s_add_u32 s48, s48, 0x100000
	s_addc_u32 s49, s49, 0
	s_mov_b32 m0, s56
	v_lshl_add_u64 v[228:229], s[48:49], 0, v[136:137]
	ds_read_b128 v[188:191], v154 offset:32768
	ds_read_b128 v[192:195], v154 offset:33792
	ds_read_b128 v[198:201], v154 offset:34816
	ds_read_b128 v[202:205], v154 offset:35840
	ds_read_b128 v[206:209], v154 offset:36864
	ds_read_b128 v[210:213], v154 offset:37888
	ds_read_b128 v[214:217], v154 offset:38912
	ds_read_b128 v[218:221], v154 offset:39936
	global_load_lds_dwordx4 v[228:229], off
	v_lshl_add_u64 v[228:229], s[48:49], 0, v[132:133]
	s_mov_b32 m0, s57
	s_nop 0
	global_load_lds_dwordx4 v[228:229], off
	s_waitcnt vmcnt(8)
	s_waitcnt lgkmcnt(0)
	s_setprio 1
	s_barrier
	v_mfma_f32_16x16x32_bf16 v[122:125], v[156:159], v[188:191], v[122:125]
	v_mfma_f32_16x16x32_bf16 v[114:117], v[164:167], v[188:191], v[114:117]
	v_mfma_f32_16x16x32_bf16 v[106:109], v[156:159], v[198:201], v[106:109]
	v_mfma_f32_16x16x32_bf16 v[98:101], v[164:167], v[198:201], v[98:101]
	v_mfma_f32_16x16x32_bf16 v[90:93], v[156:159], v[206:209], v[90:93]
	v_mfma_f32_16x16x32_bf16 v[82:85], v[164:167], v[206:209], v[82:85]
	v_mfma_f32_16x16x32_bf16 v[74:77], v[156:159], v[214:217], v[74:77]
	v_mfma_f32_16x16x32_bf16 v[66:69], v[164:167], v[214:217], v[66:69]
	v_mfma_f32_16x16x32_bf16 v[122:125], v[160:163], v[192:195], v[122:125]
	v_mfma_f32_16x16x32_bf16 v[114:117], v[168:171], v[192:195], v[114:117]
	v_mfma_f32_16x16x32_bf16 v[106:109], v[160:163], v[202:205], v[106:109]
	v_mfma_f32_16x16x32_bf16 v[98:101], v[168:171], v[202:205], v[98:101]
	v_mfma_f32_16x16x32_bf16 v[90:93], v[160:163], v[210:213], v[90:93]
	v_mfma_f32_16x16x32_bf16 v[82:85], v[168:171], v[210:213], v[82:85]
	v_mfma_f32_16x16x32_bf16 v[74:77], v[160:163], v[218:221], v[74:77]
	v_mfma_f32_16x16x32_bf16 v[66:69], v[168:171], v[218:221], v[66:69]
	s_setprio 0
	s_setprio 1
	v_mfma_f32_16x16x32_bf16 v[126:129], v[172:175], v[188:191], v[126:129]
	v_mfma_f32_16x16x32_bf16 v[118:121], v[180:183], v[188:191], v[118:121]
	v_mfma_f32_16x16x32_bf16 v[110:113], v[172:175], v[198:201], v[110:113]
	v_mfma_f32_16x16x32_bf16 v[102:105], v[180:183], v[198:201], v[102:105]
	v_mfma_f32_16x16x32_bf16 v[94:97], v[172:175], v[206:209], v[94:97]
	v_mfma_f32_16x16x32_bf16 v[86:89], v[180:183], v[206:209], v[86:89]
	v_mfma_f32_16x16x32_bf16 v[78:81], v[172:175], v[214:217], v[78:81]
	v_mfma_f32_16x16x32_bf16 v[70:73], v[180:183], v[214:217], v[70:73]
	v_mfma_f32_16x16x32_bf16 v[126:129], v[176:179], v[192:195], v[126:129]
	v_mfma_f32_16x16x32_bf16 v[118:121], v[184:187], v[192:195], v[118:121]
	v_mfma_f32_16x16x32_bf16 v[110:113], v[176:179], v[202:205], v[110:113]
	v_mfma_f32_16x16x32_bf16 v[102:105], v[184:187], v[202:205], v[102:105]
	v_mfma_f32_16x16x32_bf16 v[94:97], v[176:179], v[210:213], v[94:97]
	v_mfma_f32_16x16x32_bf16 v[86:89], v[184:187], v[210:213], v[86:89]
	v_mfma_f32_16x16x32_bf16 v[78:81], v[176:179], v[218:221], v[78:81]
	v_mfma_f32_16x16x32_bf16 v[70:73], v[184:187], v[218:221], v[70:73]
	s_setprio 0
	s_barrier
; #define PG8_STAGE(bufoff, gbase, voff) do { _Pragma("unroll") for (int _i = 0; _i < 2; ++_i) \
;         __builtin_amdgcn_global_load_lds((const unsigned*)((const char*)(gbase) + (voff)[_i]), (PG8_LAS unsigned*)(lds + (bufoff) + ldsw + _i * 8192), 16, 0, 0); } while (0)
; #define PG8_LDA(dst, b, h) do { _Pragma("unroll") for (int m = 0; m < 4; ++m) _Pragma("unroll") for (int k = 0; k < 2; ++k) dst[m][k] = *(const PG8_LAS bf16x8*)(lds + PG8_SA(b, h) + aoff + m * 2048 + k * 1024); } while (0)
; #define PG8_MMA(ai, bj, At, Bt) do { __builtin_amdgcn_s_setprio(1); _Pragma("unroll") for (int m = 0; m < 4; ++m) _Pragma("unroll") for (int n = 0; n < 2; ++n) _Pragma("unroll") for (int k = 0; k < 2; ++k) \
;         acc[ai][bj][m][n] = __builtin_amdgcn_mfma_f32_16x16x32_bf16(Bt[n][k], At[m][k], acc[ai][bj][m][n], 0, 0, 0); __builtin_amdgcn_s_setprio(0); } while (0)
; #define PG8_WAIT_V(n) asm volatile("s_waitcnt vmcnt(" #n ")" ::: "memory")
; #define PG8_WAIT_L(n) asm volatile("s_waitcnt lgkmcnt(" #n ")" ::: "memory")
; #define PG8_BAR __builtin_amdgcn_s_barrier()
; #define PG8_SCHED __builtin_amdgcn_sched_barrier(0)
; template <class Epi, class Sched, bool ALIGN_EPI = false, bool SP2 = false>
; __device__ __forceinline__ void gemm_phase(PG8_LAS unsigned char* lds, const Gemm g, const Sched& S, const Epi& E) {
;     ...
;         for (int t = 0; t < nt; t += 2) {
;     ...
;             PG8_LDA(At, 1, 1); PG8_STAGE(PG8_SB(1, 0), b3, voffB); PG8_STAGE(PG8_SB(1, 1), b3 + hstep, voffB); PG8_STAGE(PG8_SA(1, 0), a3, voffA);
;             PG8_WAIT_V(8); PG8_WAIT_L(0); PG8_BAR; PG8_MMA(1, 0, At, B0); PG8_MMA(1, 1, At, B1); PG8_BAR; PG8_SCHED;
	s_add_i32 s48, s75, s52
	v_lshl_add_u64 v[146:147], v[146:147], 0, s[12:13]
	s_mov_b32 m0, s48
	ds_read_b128 v[188:191], v154 offset:49152
	ds_read_b128 v[192:195], v154 offset:50176
	ds_read_b128 v[198:201], v154 offset:51200
	ds_read_b128 v[202:205], v154 offset:52224
	ds_read_b128 v[206:209], v154 offset:53248
	ds_read_b128 v[210:213], v154 offset:54272
	ds_read_b128 v[214:217], v154 offset:55296
	ds_read_b128 v[218:221], v154 offset:56320
	global_load_lds_dwordx4 v[146:147], off
	s_add_i32 m0, s48, 0x2000
	s_add_u32 s46, s46, 0x100080
	v_lshl_add_u64 v[146:147], v[222:223], 0, s[12:13]
	s_addc_u32 s47, s47, 0
	s_add_i32 s48, s76, s52
	global_load_lds_dwordx4 v[146:147], off
	v_lshl_add_u64 v[146:147], s[46:47], 0, v[134:135]
	s_mov_b32 m0, s48
	s_nop 0
	global_load_lds_dwordx4 v[146:147], off
	v_lshl_add_u64 v[146:147], s[46:47], 0, v[130:131]
	s_add_i32 m0, s48, 0x2000
	s_nop 0
	global_load_lds_dwordx4 v[146:147], off
	v_lshl_add_u64 v[146:147], v[224:225], 0, s[12:13]
	s_mov_b32 m0, s59
	s_nop 0
	global_load_lds_dwordx4 v[146:147], off
	v_lshl_add_u64 v[146:147], v[226:227], 0, s[12:13]
	s_mov_b32 m0, s60
	s_nop 0
	global_load_lds_dwordx4 v[146:147], off
	s_waitcnt vmcnt(8)
	s_waitcnt lgkmcnt(0)
	s_setprio 1
	s_barrier
	v_mfma_f32_16x16x32_bf16 v[58:61], v[156:159], v[188:191], v[58:61]
	v_mfma_f32_16x16x32_bf16 v[50:53], v[164:167], v[188:191], v[50:53]
	v_mfma_f32_16x16x32_bf16 v[42:45], v[156:159], v[198:201], v[42:45]
	v_mfma_f32_16x16x32_bf16 v[34:37], v[164:167], v[198:201], v[34:37]
	v_mfma_f32_16x16x32_bf16 v[26:29], v[156:159], v[206:209], v[26:29]
	v_mfma_f32_16x16x32_bf16 v[18:21], v[164:167], v[206:209], v[18:21]
	v_mfma_f32_16x16x32_bf16 v[10:13], v[156:159], v[214:217], v[10:13]
	v_mfma_f32_16x16x32_bf16 v[6:9], v[164:167], v[214:217], v[6:9]
	v_mfma_f32_16x16x32_bf16 v[58:61], v[160:163], v[192:195], v[58:61]
	v_mfma_f32_16x16x32_bf16 v[50:53], v[168:171], v[192:195], v[50:53]
	v_mfma_f32_16x16x32_bf16 v[42:45], v[160:163], v[202:205], v[42:45]
	v_mfma_f32_16x16x32_bf16 v[34:37], v[168:171], v[202:205], v[34:37]
	v_mfma_f32_16x16x32_bf16 v[26:29], v[160:163], v[210:213], v[26:29]
	v_mfma_f32_16x16x32_bf16 v[18:21], v[168:171], v[210:213], v[18:21]
	v_mfma_f32_16x16x32_bf16 v[10:13], v[160:163], v[218:221], v[10:13]
	v_mfma_f32_16x16x32_bf16 v[6:9], v[168:171], v[218:221], v[6:9]
	s_setprio 0
	s_setprio 1
	v_mfma_f32_16x16x32_bf16 v[62:65], v[172:175], v[188:191], v[62:65]
	v_mfma_f32_16x16x32_bf16 v[54:57], v[180:183], v[188:191], v[54:57]
	v_mfma_f32_16x16x32_bf16 v[46:49], v[172:175], v[198:201], v[46:49]
	v_mfma_f32_16x16x32_bf16 v[38:41], v[180:183], v[198:201], v[38:41]
	v_mfma_f32_16x16x32_bf16 v[30:33], v[172:175], v[206:209], v[30:33]
	v_mfma_f32_16x16x32_bf16 v[22:25], v[180:183], v[206:209], v[22:25]
	v_mfma_f32_16x16x32_bf16 v[14:17], v[172:175], v[214:217], v[14:17]
	v_mfma_f32_16x16x32_bf16 v[2:5], v[180:183], v[214:217], v[2:5]
	v_mfma_f32_16x16x32_bf16 v[62:65], v[176:179], v[192:195], v[62:65]
	v_mfma_f32_16x16x32_bf16 v[54:57], v[184:187], v[192:195], v[54:57]
	v_mfma_f32_16x16x32_bf16 v[46:49], v[176:179], v[202:205], v[46:49]
	v_mfma_f32_16x16x32_bf16 v[38:41], v[184:187], v[202:205], v[38:41]
	v_mfma_f32_16x16x32_bf16 v[30:33], v[176:179], v[210:213], v[30:33]
	v_mfma_f32_16x16x32_bf16 v[22:25], v[184:187], v[210:213], v[22:25]
	v_mfma_f32_16x16x32_bf16 v[14:17], v[176:179], v[218:221], v[14:17]
	v_mfma_f32_16x16x32_bf16 v[2:5], v[184:187], v[218:221], v[2:5]
	s_setprio 0
	s_barrier
	s_add_i32 s74, s74, 2
	s_add_u32 s44, s44, 0x100
	s_addc_u32 s45, s45, 0
	s_add_u32 s72, s72, 0x100
	s_addc_u32 s73, s73, 0
	s_cmp_gt_u32 s74, 61

; #define PG8_STAGE(bufoff, gbase, voff) do { _Pragma("unroll") for (int _i = 0; _i < 2; ++_i) \
;         __builtin_amdgcn_global_load_lds((const unsigned*)((const char*)(gbase) + (voff)[_i]), (PG8_LAS unsigned*)(lds + (bufoff) + ldsw + _i * 8192), 16, 0, 0); } while (0)
; #define PG8_LDA(dst, b, h) do { _Pragma("unroll") for (int m = 0; m < 4; ++m) _Pragma("unroll") for (int k = 0; k < 2; ++k) dst[m][k] = *(const PG8_LAS bf16x8*)(lds + PG8_SA(b, h) + aoff + m * 2048 + k * 1024); } while (0)
; #define PG8_WAIT_V(n) asm volatile("s_waitcnt vmcnt(" #n ")" ::: "memory")
; #define PG8_WAIT_L(n) asm volatile("s_waitcnt lgkmcnt(" #n ")" ::: "memory")
; template <class Epi, class Sched, bool ALIGN_EPI = false, bool SP2 = false>
; __device__ __forceinline__ void gemm_phase(PG8_LAS unsigned char* lds, const Gemm g, const Sched& S, const Epi& E) {
;     ...
;         const bool has_next = S.next(ui + 1, nxt);
;         const char* nA = has_next ? (const char*)g.A + (size_t)nxt.pm * tstep : cA; const char* nB = has_next ? (const char*)g.Bt + (size_t)nxt.pn * tstep : cB;
;         for (int t = 0; t < nt; t += 2) {
;             const bool last = (t == nt - 2);
;             const char* a1 = cA + (size_t)(t + 1) * kstep;
;             const char* a2 = last ? nA : cA + (size_t)(t + 2) * kstep; const char* b2 = last ? nB : cB + (size_t)(t + 2) * kstep;
;             const char* a3 = a2 + kstep; const char* b3 = b2 + kstep;
;             if (last && has_next) S.a_ready(nxt);
;             if constexpr (SP2) {
;             PG8_LDB(B0, 0, 0); PG8_LDB(B1, 0, 1); PG8_SCHED; PG8_LDA(At, 0, 0); PG8_STAGE(PG8_SA(1, 1), a1 + hstep, voffA);
;             PG8_WAIT_V(8); PG8_WAIT_L(0); PG8_BAR; PG8_MMA(0, 0, At, B0); PG8_MMA(0, 1, At, B1); PG8_BAR; PG8_SCHED;
;             PG8_LDA(At, 0, 1); PG8_STAGE(PG8_SB(0, 0), b2, voffB); PG8_STAGE(PG8_SB(0, 1), b2 + hstep, voffB); PG8_STAGE(PG8_SA(0, 0), a2, voffA);
;             PG8_WAIT_V(8); PG8_WAIT_L(0); PG8_BAR; PG8_MMA(1, 0, At, B0); PG8_MMA(1, 1, At, B1); PG8_BAR; PG8_SCHED;
;     ...
; #pragma unroll
;         for (int a = 0; a < 2; ++a)
; #pragma unroll
;             for (int b = 0; b < 2; ++b)
; #pragma unroll
;                 for (int m = 0; m < 4; ++m)
; #pragma unroll
;                     for (int n = 0; n < 2; ++n) acc[a][b][m][n] = (f32x4){0.f, 0.f, 0.f, 0.f};
;         cur = nxt; cA = nA; cB = nB; ++ui;
.LBB0_983:
	s_add_u32 s42, s42, 0x2b0080
	s_addc_u32 s43, s43, 0
	s_add_u32 s69, s44, 0x100
	s_addc_u32 s70, s45, 0
	s_mov_b32 s71, -2
	s_waitcnt lgkmcnt(0)
	ds_read_b128 v[146:149], v160
	ds_read_b128 v[164:167], v160 offset:1024
	ds_read_b128 v[168:171], v160 offset:2048
	ds_read_b128 v[172:175], v160 offset:3072
	ds_read_b128 v[176:179], v161
	ds_read_b128 v[180:183], v161 offset:1024
	ds_read_b128 v[184:187], v161 offset:2048
	ds_read_b128 v[188:191], v161 offset:3072
	s_add_u32 s44, s42, 0xffd50080
	s_addc_u32 s45, s43, -1
	s_cmpk_eq_i32 s71, 0xa8
	s_cselect_b32 s47, s7, s45
	s_cselect_b32 s46, s6, s44
	s_cselect_b32 s45, s41, s70
	s_cselect_b32 s44, s40, s69
	v_lshl_add_u64 v[226:227], s[42:43], 0, v[138:139]
	s_add_i32 m0, s52, 0xc000
	ds_read_b128 v[192:195], v162
	ds_read_b128 v[198:201], v162 offset:1024
	ds_read_b128 v[202:205], v162 offset:2048
	ds_read_b128 v[206:209], v162 offset:3072
	ds_read_b128 v[210:213], v162 offset:4096
	ds_read_b128 v[214:217], v162 offset:5120
	ds_read_b128 v[218:221], v162 offset:6144
	ds_read_b128 v[222:225], v162 offset:7168
	global_load_lds_dwordx4 v[226:227], off
	v_lshl_add_u64 v[226:227], s[42:43], 0, v[140:141]
	s_add_i32 m0, s52, 0xe000
	s_nop 0
	global_load_lds_dwordx4 v[226:227], off
	s_waitcnt vmcnt(8)
	s_waitcnt lgkmcnt(0)
	s_setprio 1
	s_barrier
	v_mfma_f32_16x16x32_bf16 v[126:129], v[146:149], v[192:195], 0
	v_mfma_f32_16x16x32_bf16 v[122:125], v[168:171], v[192:195], 0
	v_mfma_f32_16x16x32_bf16 v[110:113], v[146:149], v[202:205], 0
	v_mfma_f32_16x16x32_bf16 v[106:109], v[168:171], v[202:205], 0
	v_mfma_f32_16x16x32_bf16 v[94:97], v[146:149], v[210:213], 0
	v_mfma_f32_16x16x32_bf16 v[90:93], v[168:171], v[210:213], 0
	v_mfma_f32_16x16x32_bf16 v[78:81], v[146:149], v[218:221], 0
	v_mfma_f32_16x16x32_bf16 v[74:77], v[168:171], v[218:221], 0
	v_mfma_f32_16x16x32_bf16 v[126:129], v[164:167], v[198:201], v[126:129]
	v_mfma_f32_16x16x32_bf16 v[122:125], v[172:175], v[198:201], v[122:125]
	v_mfma_f32_16x16x32_bf16 v[110:113], v[164:167], v[206:209], v[110:113]
	v_mfma_f32_16x16x32_bf16 v[106:109], v[172:175], v[206:209], v[106:109]
	v_mfma_f32_16x16x32_bf16 v[94:97], v[164:167], v[214:217], v[94:97]
	v_mfma_f32_16x16x32_bf16 v[90:93], v[172:175], v[214:217], v[90:93]
	v_mfma_f32_16x16x32_bf16 v[78:81], v[164:167], v[222:225], v[78:81]
	v_mfma_f32_16x16x32_bf16 v[74:77], v[172:175], v[222:225], v[74:77]
	s_setprio 0
	s_setprio 1
	v_mfma_f32_16x16x32_bf16 v[118:121], v[176:179], v[192:195], 0
	v_mfma_f32_16x16x32_bf16 v[114:117], v[184:187], v[192:195], 0
	v_mfma_f32_16x16x32_bf16 v[102:105], v[176:179], v[202:205], 0
	v_mfma_f32_16x16x32_bf16 v[98:101], v[184:187], v[202:205], 0
	v_mfma_f32_16x16x32_bf16 v[86:89], v[176:179], v[210:213], 0
	v_mfma_f32_16x16x32_bf16 v[82:85], v[184:187], v[210:213], 0
	v_mfma_f32_16x16x32_bf16 v[70:73], v[176:179], v[218:221], 0
	v_mfma_f32_16x16x32_bf16 v[66:69], v[184:187], v[218:221], 0
	v_mfma_f32_16x16x32_bf16 v[118:121], v[180:183], v[198:201], v[118:121]
	v_mfma_f32_16x16x32_bf16 v[114:117], v[188:191], v[198:201], v[114:117]
	v_mfma_f32_16x16x32_bf16 v[102:105], v[180:183], v[206:209], v[102:105]
	v_mfma_f32_16x16x32_bf16 v[98:101], v[188:191], v[206:209], v[98:101]
	v_mfma_f32_16x16x32_bf16 v[86:89], v[180:183], v[214:217], v[86:89]
	v_mfma_f32_16x16x32_bf16 v[82:85], v[188:191], v[214:217], v[82:85]
	v_mfma_f32_16x16x32_bf16 v[70:73], v[180:183], v[222:225], v[70:73]
	v_mfma_f32_16x16x32_bf16 v[66:69], v[188:191], v[222:225], v[66:69]
	s_setprio 0
	s_barrier
	s_add_i32 s72, s62, s51
	v_lshl_add_u64 v[226:227], s[44:45], 0, v[132:133]
	s_mov_b32 m0, s72
	ds_read_b128 v[192:195], v162 offset:16384
	ds_read_b128 v[198:201], v162 offset:17408
	ds_read_b128 v[202:205], v162 offset:18432
	ds_read_b128 v[206:209], v162 offset:19456
	ds_read_b128 v[210:213], v162 offset:20480
	ds_read_b128 v[214:217], v162 offset:21504
	ds_read_b128 v[218:221], v162 offset:22528
	ds_read_b128 v[222:225], v162 offset:23552
	global_load_lds_dwordx4 v[226:227], off
	s_add_i32 m0, s72, 0x2000
	s_add_u32 s72, s44, 0x2b0000
	v_lshl_add_u64 v[228:229], s[44:45], 0, v[136:137]
	s_addc_u32 s73, s45, 0
	s_add_i32 s74, s63, s51
	global_load_lds_dwordx4 v[228:229], off
	v_lshl_add_u64 v[230:231], s[72:73], 0, v[132:133]
	s_mov_b32 m0, s74
	v_lshl_add_u64 v[232:233], s[46:47], 0, v[134:135]
	global_load_lds_dwordx4 v[230:231], off
	v_lshl_add_u64 v[230:231], s[72:73], 0, v[136:137]
	s_add_i32 m0, s74, 0x2000
	s_nop 0
	global_load_lds_dwordx4 v[230:231], off
	v_lshl_add_u64 v[230:231], s[46:47], 0, v[130:131]
	s_mov_b32 m0, s52
	s_nop 0
	global_load_lds_dwordx4 v[230:231], off
	s_mov_b32 m0, s53
	s_nop 0
	global_load_lds_dwordx4 v[232:233], off
	s_waitcnt vmcnt(8)
	s_waitcnt lgkmcnt(0)
	s_setprio 1
	s_barrier
; #define PG8_STAGE(bufoff, gbase, voff) do { _Pragma("unroll") for (int _i = 0; _i < 2; ++_i) \
;         __builtin_amdgcn_global_load_lds((const unsigned*)((const char*)(gbase) + (voff)[_i]), (PG8_LAS unsigned*)(lds + (bufoff) + ldsw + _i * 8192), 16, 0, 0); } while (0)
; #define PG8_LDA(dst, b, h) do { _Pragma("unroll") for (int m = 0; m < 4; ++m) _Pragma("unroll") for (int k = 0; k < 2; ++k) dst[m][k] = *(const PG8_LAS bf16x8*)(lds + PG8_SA(b, h) + aoff + m * 2048 + k * 1024); } while (0)
; #define PG8_LDB(dst, b, h) do { _Pragma("unroll") for (int n = 0; n < 2; ++n) _Pragma("unroll") for (int k = 0; k < 2; ++k) dst[n][k] = *(const PG8_LAS bf16x8*)(lds + PG8_SB(b, h) + boff + n * 2048 + k * 1024); } while (0)
; #define PG8_MMA(ai, bj, At, Bt) do { __builtin_amdgcn_s_setprio(1); _Pragma("unroll") for (int m = 0; m < 4; ++m) _Pragma("unroll") for (int n = 0; n < 2; ++n) _Pragma("unroll") for (int k = 0; k < 2; ++k) \
;         acc[ai][bj][m][n] = __builtin_amdgcn_mfma_f32_16x16x32_bf16(Bt[n][k], At[m][k], acc[ai][bj][m][n], 0, 0, 0); __builtin_amdgcn_s_setprio(0); } while (0)
; #define PG8_WAIT_V(n) asm volatile("s_waitcnt vmcnt(" #n ")" ::: "memory")
; #define PG8_WAIT_L(n) asm volatile("s_waitcnt lgkmcnt(" #n ")" ::: "memory")
; #define PG8_BAR __builtin_amdgcn_s_barrier()
; #define PG8_SCHED __builtin_amdgcn_sched_barrier(0)
; template <class Epi, class Sched, bool ALIGN_EPI = false, bool SP2 = false>
; __device__ __forceinline__ void gemm_phase(PG8_LAS unsigned char* lds, const Gemm g, const Sched& S, const Epi& E) {
;     ...
;             PG8_WAIT_V(8); PG8_WAIT_L(0); PG8_BAR; PG8_MMA(1, 0, At, B0); PG8_MMA(1, 1, At, B1); PG8_BAR; PG8_SCHED;
;             PG8_LDB(B0, 1, 0); PG8_LDB(B1, 1, 1); PG8_SCHED; PG8_LDA(At, 1, 0); PG8_STAGE(PG8_SA(0, 1), a2 + hstep, voffA);
;             PG8_WAIT_V(8); PG8_WAIT_L(0); PG8_BAR; PG8_MMA(0, 0, At, B0); PG8_MMA(0, 1, At, B1); PG8_BAR; PG8_SCHED;
;             PG8_LDA(At, 1, 1); PG8_STAGE(PG8_SB(1, 0), b3, voffB); PG8_STAGE(PG8_SB(1, 1), b3 + hstep, voffB); PG8_STAGE(PG8_SA(1, 0), a3, voffA);
	v_mfma_f32_16x16x32_bf16 v[62:65], v[146:149], v[192:195], 0
	v_mfma_f32_16x16x32_bf16 v[58:61], v[168:171], v[192:195], 0
	v_mfma_f32_16x16x32_bf16 v[46:49], v[146:149], v[202:205], 0
	v_mfma_f32_16x16x32_bf16 v[42:45], v[168:171], v[202:205], 0
	v_mfma_f32_16x16x32_bf16 v[30:33], v[146:149], v[210:213], 0
	v_mfma_f32_16x16x32_bf16 v[26:29], v[168:171], v[210:213], 0
	v_mfma_f32_16x16x32_bf16 v[14:17], v[146:149], v[218:221], 0
	v_mfma_f32_16x16x32_bf16 v[10:13], v[168:171], v[218:221], 0
	v_mfma_f32_16x16x32_bf16 v[62:65], v[164:167], v[198:201], v[62:65]
	v_mfma_f32_16x16x32_bf16 v[58:61], v[172:175], v[198:201], v[58:61]
	v_mfma_f32_16x16x32_bf16 v[46:49], v[164:167], v[206:209], v[46:49]
	v_mfma_f32_16x16x32_bf16 v[42:45], v[172:175], v[206:209], v[42:45]
	v_mfma_f32_16x16x32_bf16 v[30:33], v[164:167], v[214:217], v[30:33]
	v_mfma_f32_16x16x32_bf16 v[26:29], v[172:175], v[214:217], v[26:29]
	v_mfma_f32_16x16x32_bf16 v[14:17], v[164:167], v[222:225], v[14:17]
	v_mfma_f32_16x16x32_bf16 v[10:13], v[172:175], v[222:225], v[10:13]
	s_setprio 0
	s_setprio 1
	v_mfma_f32_16x16x32_bf16 v[54:57], v[176:179], v[192:195], 0
	v_mfma_f32_16x16x32_bf16 v[50:53], v[184:187], v[192:195], 0
	v_mfma_f32_16x16x32_bf16 v[38:41], v[176:179], v[202:205], 0
	v_mfma_f32_16x16x32_bf16 v[34:37], v[184:187], v[202:205], 0
	v_mfma_f32_16x16x32_bf16 v[22:25], v[176:179], v[210:213], 0
	v_mfma_f32_16x16x32_bf16 v[18:21], v[184:187], v[210:213], 0
	v_mfma_f32_16x16x32_bf16 v[6:9], v[176:179], v[218:221], 0
	v_mfma_f32_16x16x32_bf16 v[2:5], v[184:187], v[218:221], 0
	v_mfma_f32_16x16x32_bf16 v[54:57], v[180:183], v[198:201], v[54:57]
	v_mfma_f32_16x16x32_bf16 v[50:53], v[188:191], v[198:201], v[50:53]
	v_mfma_f32_16x16x32_bf16 v[38:41], v[180:183], v[206:209], v[38:41]
	v_mfma_f32_16x16x32_bf16 v[34:37], v[188:191], v[206:209], v[34:37]
	v_mfma_f32_16x16x32_bf16 v[22:25], v[180:183], v[214:217], v[22:25]
	v_mfma_f32_16x16x32_bf16 v[18:21], v[188:191], v[214:217], v[18:21]
	v_mfma_f32_16x16x32_bf16 v[6:9], v[180:183], v[222:225], v[6:9]
	v_mfma_f32_16x16x32_bf16 v[2:5], v[188:191], v[222:225], v[2:5]
	s_setprio 0
	s_barrier
	s_add_i32 s72, 0, 0x18000
	s_add_i32 s73, 0, 0x1c000
	v_add_u32_e32 v172, s72, v151
	v_add_u32_e32 v188, s73, v151
	ds_read_b128 v[146:149], v172
	ds_read_b128 v[164:167], v172 offset:1024
	ds_read_b128 v[168:171], v172 offset:2048
	ds_read_b128 v[172:175], v172 offset:3072
	ds_read_b128 v[176:179], v188
	ds_read_b128 v[180:183], v188 offset:1024
	ds_read_b128 v[184:187], v188 offset:2048
	ds_read_b128 v[188:191], v188 offset:3072
	s_add_u32 s46, s46, 0x2b0000
	s_addc_u32 s47, s47, 0
	s_mov_b32 m0, s54
	v_lshl_add_u64 v[234:235], s[46:47], 0, v[130:131]
	ds_read_b128 v[192:195], v162 offset:32768
	ds_read_b128 v[198:201], v162 offset:33792
	ds_read_b128 v[202:205], v162 offset:34816
	ds_read_b128 v[206:209], v162 offset:35840
	ds_read_b128 v[210:213], v162 offset:36864
	ds_read_b128 v[214:217], v162 offset:37888
	ds_read_b128 v[218:221], v162 offset:38912
	ds_read_b128 v[222:225], v162 offset:39936
	global_load_lds_dwordx4 v[234:235], off
	v_lshl_add_u64 v[234:235], s[46:47], 0, v[134:135]
	s_mov_b32 m0, s55
	s_nop 0
	global_load_lds_dwordx4 v[234:235], off
	s_waitcnt vmcnt(8)
	s_waitcnt lgkmcnt(0)
	s_setprio 1
	s_barrier
	v_mfma_f32_16x16x32_bf16 v[126:129], v[146:149], v[192:195], v[126:129]
	v_mfma_f32_16x16x32_bf16 v[122:125], v[168:171], v[192:195], v[122:125]
	v_mfma_f32_16x16x32_bf16 v[110:113], v[146:149], v[202:205], v[110:113]
	v_mfma_f32_16x16x32_bf16 v[106:109], v[168:171], v[202:205], v[106:109]
	v_mfma_f32_16x16x32_bf16 v[94:97], v[146:149], v[210:213], v[94:97]
	v_mfma_f32_16x16x32_bf16 v[90:93], v[168:171], v[210:213], v[90:93]
	v_mfma_f32_16x16x32_bf16 v[78:81], v[146:149], v[218:221], v[78:81]
	v_mfma_f32_16x16x32_bf16 v[74:77], v[168:171], v[218:221], v[74:77]
	v_mfma_f32_16x16x32_bf16 v[126:129], v[164:167], v[198:201], v[126:129]
	v_mfma_f32_16x16x32_bf16 v[122:125], v[172:175], v[198:201], v[122:125]
	v_mfma_f32_16x16x32_bf16 v[110:113], v[164:167], v[206:209], v[110:113]
	v_mfma_f32_16x16x32_bf16 v[106:109], v[172:175], v[206:209], v[106:109]
	v_mfma_f32_16x16x32_bf16 v[94:97], v[164:167], v[214:217], v[94:97]
	v_mfma_f32_16x16x32_bf16 v[90:93], v[172:175], v[214:217], v[90:93]
	v_mfma_f32_16x16x32_bf16 v[78:81], v[164:167], v[222:225], v[78:81]
	v_mfma_f32_16x16x32_bf16 v[74:77], v[172:175], v[222:225], v[74:77]
	s_setprio 0
	s_setprio 1
	v_mfma_f32_16x16x32_bf16 v[118:121], v[176:179], v[192:195], v[118:121]
	v_mfma_f32_16x16x32_bf16 v[114:117], v[184:187], v[192:195], v[114:117]
	v_mfma_f32_16x16x32_bf16 v[102:105], v[176:179], v[202:205], v[102:105]
	v_mfma_f32_16x16x32_bf16 v[98:101], v[184:187], v[202:205], v[98:101]
	v_mfma_f32_16x16x32_bf16 v[86:89], v[176:179], v[210:213], v[86:89]
	v_mfma_f32_16x16x32_bf16 v[82:85], v[184:187], v[210:213], v[82:85]
	v_mfma_f32_16x16x32_bf16 v[70:73], v[176:179], v[218:221], v[70:73]
	v_mfma_f32_16x16x32_bf16 v[66:69], v[184:187], v[218:221], v[66:69]
	v_mfma_f32_16x16x32_bf16 v[118:121], v[180:183], v[198:201], v[118:121]
	v_mfma_f32_16x16x32_bf16 v[114:117], v[188:191], v[198:201], v[114:117]
	v_mfma_f32_16x16x32_bf16 v[102:105], v[180:183], v[206:209], v[102:105]
	v_mfma_f32_16x16x32_bf16 v[98:101], v[188:191], v[206:209], v[98:101]
	v_mfma_f32_16x16x32_bf16 v[86:89], v[180:183], v[214:217], v[86:89]
	v_mfma_f32_16x16x32_bf16 v[82:85], v[188:191], v[214:217], v[82:85]
	v_mfma_f32_16x16x32_bf16 v[70:73], v[180:183], v[222:225], v[70:73]
	v_mfma_f32_16x16x32_bf16 v[66:69], v[188:191], v[222:225], v[66:69]
	s_setprio 0
	s_barrier
; #define PG8_STAGE(bufoff, gbase, voff) do { _Pragma("unroll") for (int _i = 0; _i < 2; ++_i) \
;         __builtin_amdgcn_global_load_lds((const unsigned*)((const char*)(gbase) + (voff)[_i]), (PG8_LAS unsigned*)(lds + (bufoff) + ldsw + _i * 8192), 16, 0, 0); } while (0)
; #define PG8_LDA(dst, b, h) do { _Pragma("unroll") for (int m = 0; m < 4; ++m) _Pragma("unroll") for (int k = 0; k < 2; ++k) dst[m][k] = *(const PG8_LAS bf16x8*)(lds + PG8_SA(b, h) + aoff + m * 2048 + k * 1024); } while (0)
; #define PG8_MMA(ai, bj, At, Bt) do { __builtin_amdgcn_s_setprio(1); _Pragma("unroll") for (int m = 0; m < 4; ++m) _Pragma("unroll") for (int n = 0; n < 2; ++n) _Pragma("unroll") for (int k = 0; k < 2; ++k) \
;         acc[ai][bj][m][n] = __builtin_amdgcn_mfma_f32_16x16x32_bf16(Bt[n][k], At[m][k], acc[ai][bj][m][n], 0, 0, 0); __builtin_amdgcn_s_setprio(0); } while (0)
; #define PG8_WAIT_V(n) asm volatile("s_waitcnt vmcnt(" #n ")" ::: "memory")
; #define PG8_WAIT_L(n) asm volatile("s_waitcnt lgkmcnt(" #n ")" ::: "memory")
; #define PG8_BAR __builtin_amdgcn_s_barrier()
; #define PG8_SCHED __builtin_amdgcn_sched_barrier(0)
; template <class Epi, class Sched, bool ALIGN_EPI = false, bool SP2 = false>
; __device__ __forceinline__ void gemm_phase(PG8_LAS unsigned char* lds, const Gemm g, const Sched& S, const Epi& E) {
;     ...
;         for (int t = 0; t < nt; t += 2) {
;     ...
;             PG8_LDA(At, 1, 1); PG8_STAGE(PG8_SB(1, 0), b3, voffB); PG8_STAGE(PG8_SB(1, 1), b3 + hstep, voffB); PG8_STAGE(PG8_SA(1, 0), a3, voffA);
;             PG8_WAIT_V(8); PG8_WAIT_L(0); PG8_BAR; PG8_MMA(1, 0, At, B0); PG8_MMA(1, 1, At, B1); PG8_BAR; PG8_SCHED;
	s_add_i32 s46, s72, s51
	v_lshl_add_u64 v[226:227], v[226:227], 0, s[36:37]
	s_mov_b32 m0, s46
	ds_read_b128 v[192:195], v162 offset:49152
	ds_read_b128 v[198:201], v162 offset:50176
	ds_read_b128 v[202:205], v162 offset:51200
	ds_read_b128 v[206:209], v162 offset:52224
	ds_read_b128 v[210:213], v162 offset:53248
	ds_read_b128 v[214:217], v162 offset:54272
	ds_read_b128 v[218:221], v162 offset:55296
	ds_read_b128 v[222:225], v162 offset:56320
	global_load_lds_dwordx4 v[226:227], off
	s_add_i32 m0, s46, 0x2000
	s_add_u32 s44, s44, 0x2b0080
	v_lshl_add_u64 v[226:227], v[228:229], 0, s[36:37]
	s_addc_u32 s45, s45, 0
	s_add_i32 s46, s73, s51
	global_load_lds_dwordx4 v[226:227], off
	v_lshl_add_u64 v[226:227], s[44:45], 0, v[132:133]
	s_mov_b32 m0, s46
	s_nop 0
	global_load_lds_dwordx4 v[226:227], off
	v_lshl_add_u64 v[226:227], s[44:45], 0, v[136:137]
	s_add_i32 m0, s46, 0x2000
	s_nop 0
	global_load_lds_dwordx4 v[226:227], off
	v_lshl_add_u64 v[226:227], v[230:231], 0, s[36:37]
	s_mov_b32 m0, s57
	s_nop 0
	global_load_lds_dwordx4 v[226:227], off
	v_lshl_add_u64 v[226:227], v[232:233], 0, s[36:37]
	s_mov_b32 m0, s58
	s_nop 0
	global_load_lds_dwordx4 v[226:227], off
	s_waitcnt vmcnt(8)
	s_waitcnt lgkmcnt(0)
	s_setprio 1
	s_barrier
	v_mfma_f32_16x16x32_bf16 v[62:65], v[146:149], v[192:195], v[62:65]
	v_mfma_f32_16x16x32_bf16 v[58:61], v[168:171], v[192:195], v[58:61]
	v_mfma_f32_16x16x32_bf16 v[46:49], v[146:149], v[202:205], v[46:49]
	v_mfma_f32_16x16x32_bf16 v[42:45], v[168:171], v[202:205], v[42:45]
	v_mfma_f32_16x16x32_bf16 v[30:33], v[146:149], v[210:213], v[30:33]
	v_mfma_f32_16x16x32_bf16 v[26:29], v[168:171], v[210:213], v[26:29]
	v_mfma_f32_16x16x32_bf16 v[14:17], v[146:149], v[218:221], v[14:17]
	v_mfma_f32_16x16x32_bf16 v[10:13], v[168:171], v[218:221], v[10:13]
	v_mfma_f32_16x16x32_bf16 v[62:65], v[164:167], v[198:201], v[62:65]
	v_mfma_f32_16x16x32_bf16 v[58:61], v[172:175], v[198:201], v[58:61]
	v_mfma_f32_16x16x32_bf16 v[46:49], v[164:167], v[206:209], v[46:49]
	v_mfma_f32_16x16x32_bf16 v[42:45], v[172:175], v[206:209], v[42:45]
	v_mfma_f32_16x16x32_bf16 v[30:33], v[164:167], v[214:217], v[30:33]
	v_mfma_f32_16x16x32_bf16 v[26:29], v[172:175], v[214:217], v[26:29]
	v_mfma_f32_16x16x32_bf16 v[14:17], v[164:167], v[222:225], v[14:17]
	v_mfma_f32_16x16x32_bf16 v[10:13], v[172:175], v[222:225], v[10:13]
	s_setprio 0
	s_setprio 1
	v_mfma_f32_16x16x32_bf16 v[54:57], v[176:179], v[192:195], v[54:57]
	v_mfma_f32_16x16x32_bf16 v[50:53], v[184:187], v[192:195], v[50:53]
	v_mfma_f32_16x16x32_bf16 v[38:41], v[176:179], v[202:205], v[38:41]
	v_mfma_f32_16x16x32_bf16 v[34:37], v[184:187], v[202:205], v[34:37]
	v_mfma_f32_16x16x32_bf16 v[22:25], v[176:179], v[210:213], v[22:25]
	v_mfma_f32_16x16x32_bf16 v[18:21], v[184:187], v[210:213], v[18:21]
	v_mfma_f32_16x16x32_bf16 v[6:9], v[176:179], v[218:221], v[6:9]
	v_mfma_f32_16x16x32_bf16 v[2:5], v[184:187], v[218:221], v[2:5]
	v_mfma_f32_16x16x32_bf16 v[54:57], v[180:183], v[198:201], v[54:57]
	v_mfma_f32_16x16x32_bf16 v[50:53], v[188:191], v[198:201], v[50:53]
	v_mfma_f32_16x16x32_bf16 v[38:41], v[180:183], v[206:209], v[38:41]
	v_mfma_f32_16x16x32_bf16 v[34:37], v[188:191], v[206:209], v[34:37]
	v_mfma_f32_16x16x32_bf16 v[22:25], v[180:183], v[214:217], v[22:25]
	v_mfma_f32_16x16x32_bf16 v[18:21], v[188:191], v[214:217], v[18:21]
	v_mfma_f32_16x16x32_bf16 v[6:9], v[180:183], v[222:225], v[6:9]
	v_mfma_f32_16x16x32_bf16 v[2:5], v[188:191], v[222:225], v[2:5]
	s_setprio 0
	s_barrier
	s_add_i32 s71, s71, 2
	s_add_u32 s42, s42, 0x100
	s_addc_u32 s43, s43, 0
	s_add_u32 s69, s69, 0x100
	s_addc_u32 s70, s70, 0
	s_cmpk_gt_u32 s71, 0xa9
